# plus: residual epilogue row sums via v_permlane16/32_swap instead of ds_bpermute
# baseline (speedup 1.0000x reference)
.LBB0_275:
	v_lshl_or_b32 v204, s52, 8, v244
	v_lshl_add_u32 v234, s53, 8, v242
	v_ashrrev_i32_e32 v205, 31, v204
	v_lshlrev_b64 v[236:237], 1, v[204:205]
	v_ashrrev_i32_e32 v235, 31, v234
	v_lshl_add_u64 v[124:125], s[12:13], 0, v[236:237]
	v_lshlrev_b64 v[238:239], 11, v[234:235]
	v_lshl_add_u64 v[120:121], v[124:125], 0, v[238:239]
	global_load_dwordx4 v[188:191], v[120:121], off
	global_load_dwordx4 v[184:187], v[120:121], off offset:256
	v_or_b32_e32 v230, 16, v234
	v_ashrrev_i32_e32 v231, 31, v230
	v_or_b32_e32 v226, 32, v234
	v_lshlrev_b64 v[232:233], 11, v[230:231]
	v_ashrrev_i32_e32 v227, 31, v226
	v_or_b32_e32 v222, 48, v234
	v_lshl_add_u64 v[120:121], v[124:125], 0, v[232:233]
	v_lshlrev_b64 v[228:229], 11, v[226:227]
	v_ashrrev_i32_e32 v223, 31, v222
	v_add_u32_e32 v218, 0x80, v234
	global_load_dwordx4 v[180:183], v[120:121], off
	global_load_dwordx4 v[176:179], v[120:121], off offset:256
	v_lshl_add_u64 v[120:121], v[124:125], 0, v[228:229]
	v_lshlrev_b64 v[224:225], 11, v[222:223]
	v_ashrrev_i32_e32 v219, 31, v218
	v_add_u32_e32 v214, 0x90, v234
	global_load_dwordx4 v[172:175], v[120:121], off
	global_load_dwordx4 v[168:171], v[120:121], off offset:256
	v_lshl_add_u64 v[120:121], v[124:125], 0, v[224:225]
	v_lshlrev_b64 v[220:221], 11, v[218:219]
	v_ashrrev_i32_e32 v215, 31, v214
	v_add_u32_e32 v210, 0xa0, v234
	v_add_u32_e32 v206, 0xb0, v234
	global_load_dwordx4 v[164:167], v[120:121], off
	global_load_dwordx4 v[160:163], v[120:121], off offset:256
	v_lshl_add_u64 v[120:121], v[124:125], 0, v[220:221]
	v_lshlrev_b64 v[216:217], 11, v[214:215]
	v_ashrrev_i32_e32 v211, 31, v210
	v_ashrrev_i32_e32 v207, 31, v206
	global_load_dwordx4 v[156:159], v[120:121], off
	global_load_dwordx4 v[152:155], v[120:121], off offset:256
	v_lshl_add_u64 v[120:121], v[124:125], 0, v[216:217]
	v_lshlrev_b64 v[212:213], 11, v[210:211]
	v_lshlrev_b64 v[208:209], 11, v[206:207]
	global_load_dwordx4 v[148:151], v[120:121], off
	global_load_dwordx4 v[144:147], v[120:121], off offset:256
	v_lshl_add_u64 v[120:121], v[124:125], 0, v[212:213]
	v_lshl_add_u64 v[124:125], v[124:125], 0, v[208:209]
	global_load_dwordx4 v[128:131], v[120:121], off
	s_nop 0
	global_load_dwordx4 v[120:123], v[120:121], off offset:256
	s_nop 0
	global_load_dwordx4 v[132:135], v[124:125], off
	s_nop 0
	global_load_dwordx4 v[124:127], v[124:125], off offset:256
	v_lshl_add_u64 v[238:239], s[12:13], 0, v[238:239]
	v_lshl_add_u64 v[236:237], v[238:239], 0, v[236:237]
	s_lshl_b32 s86, s52, 2
	s_ashr_i32 s87, s86, 31
	s_waitcnt vmcnt(0)
	v_lshlrev_b32_e32 v250, 16, v188
	v_and_b32_e32 v251, 0xffff0000, v188
	v_lshlrev_b32_e32 v188, 16, v189
	v_and_b32_e32 v189, 0xffff0000, v189
	v_lshlrev_b32_e32 v252, 16, v190
	v_and_b32_e32 v253, 0xffff0000, v190
	v_lshlrev_b32_e32 v190, 16, v191
	v_and_b32_e32 v191, 0xffff0000, v191
	v_pk_fma_f32 v[142:143], v[142:143], 0.5, v[188:189] op_sel_hi:[1,0,1]
	v_pk_fma_f32 v[140:141], v[140:141], 0.5, v[250:251] op_sel_hi:[1,0,1]
	v_pk_fma_f32 v[188:189], v[138:139], 0.5, v[190:191] op_sel_hi:[1,0,1]
	v_pk_fma_f32 v[190:191], v[136:137], 0.5, v[252:253] op_sel_hi:[1,0,1]
	v_cvt_pk_bf16_f32 v136, v140, v141
	v_cvt_pk_bf16_f32 v137, v142, v143
	s_nop 0
	v_cvt_pk_bf16_f32 v138, v190, v191
	v_cvt_pk_bf16_f32 v139, v188, v189
	global_store_dwordx4 v[236:237], v[136:139], off
	s_nop 1
	v_pk_fma_f32 v[136:137], v[140:141], v[140:141], 0 op_sel_hi:[1,1,0]
	v_pk_fma_f32 v[138:139], v[142:143], v[142:143], 0 op_sel_hi:[1,1,0]
	v_lshlrev_b32_e32 v140, 16, v184
	v_and_b32_e32 v141, 0xffff0000, v184
	v_lshlrev_b32_e32 v142, 16, v185
	v_and_b32_e32 v143, 0xffff0000, v185
	v_lshlrev_b32_e32 v184, 16, v186
	v_and_b32_e32 v185, 0xffff0000, v186
	v_lshlrev_b32_e32 v186, 16, v187
	v_and_b32_e32 v187, 0xffff0000, v187
	v_pk_fma_f32 v[138:139], v[188:189], v[188:189], v[138:139]
	v_pk_fma_f32 v[136:137], v[190:191], v[190:191], v[136:137]
	v_pk_fma_f32 v[118:119], v[118:119], 0.5, v[142:143] op_sel_hi:[1,0,1]
	v_pk_fma_f32 v[116:117], v[116:117], 0.5, v[140:141] op_sel_hi:[1,0,1]
	v_pk_fma_f32 v[140:141], v[114:115], 0.5, v[186:187] op_sel_hi:[1,0,1]
	v_pk_fma_f32 v[142:143], v[112:113], 0.5, v[184:185] op_sel_hi:[1,0,1]
	v_cvt_pk_bf16_f32 v112, v116, v117
	v_cvt_pk_bf16_f32 v113, v118, v119
	s_nop 0
	v_cvt_pk_bf16_f32 v114, v142, v143
	v_cvt_pk_bf16_f32 v115, v140, v141
	global_store_dwordx4 v[236:237], v[112:115], off offset:256
	s_nop 1
	v_pk_fma_f32 v[112:113], v[116:117], v[116:117], v[136:137]
	v_pk_fma_f32 v[114:115], v[118:119], v[118:119], v[138:139]
	v_pk_fma_f32 v[112:113], v[142:143], v[142:143], v[112:113]
	v_pk_fma_f32 v[114:115], v[140:141], v[140:141], v[114:115]
	v_add_f32_e32 v112, v112, v113
	v_add_f32_e32 v113, v114, v115
	v_and_b32_e32 v114, 64, v248
	v_add_f32_e32 v113, v112, v113
	v_xor_b32_e32 v112, 16, v248
	v_add_u32_e32 v115, 64, v114
	v_cmp_lt_i32_e32 vcc, v112, v115
	s_nop 1
	v_cndmask_b32_e32 v112, v248, v112, vcc
	v_lshlrev_b32_e32 v112, 2, v112
	v_mov_b32_e32 v114, v113
	s_nop 1
	v_permlane16_swap_b32 v114, v113
	s_waitcnt lgkmcnt(0)
	v_add_f32_e32 v114, v113, v114
	v_xor_b32_e32 v113, 32, v248
	v_cmp_lt_i32_e32 vcc, v113, v115
	s_nop 1
	v_cndmask_b32_e32 v113, v248, v113, vcc
	v_lshlrev_b32_e32 v113, 2, v113
	v_mov_b32_e32 v115, v114
	s_nop 1
	v_permlane32_swap_b32 v115, v114
	s_and_saveexec_b64 s[52:53], s[6:7]
	s_cbranch_execz .LBB0_277
	v_lshlrev_b64 v[116:117], 6, v[234:235]
	v_lshl_add_u64 v[116:117], s[70:71], 0, v[116:117]
	v_lshl_add_u64 v[116:117], s[86:87], 2, v[116:117]
	s_lshl_b32 s76, s20, 2
	v_lshl_add_u64 v[116:117], v[116:117], 0, s[76:77]
	s_waitcnt lgkmcnt(0)
	v_add_f32_e32 v114, v114, v115
	global_store_dword v[116:117], v114, off
.LBB0_277:
	s_or_b64 exec, exec, s[52:53]
	v_lshlrev_b32_e32 v114, 16, v180
	s_waitcnt lgkmcnt(0)
	v_and_b32_e32 v115, 0xffff0000, v180
	v_lshlrev_b32_e32 v116, 16, v181
	v_and_b32_e32 v117, 0xffff0000, v181
	v_lshlrev_b32_e32 v118, 16, v182
	v_and_b32_e32 v119, 0xffff0000, v182
	v_lshlrev_b32_e32 v136, 16, v183
	v_and_b32_e32 v137, 0xffff0000, v183
	v_pk_fma_f32 v[110:111], v[110:111], 0.5, v[116:117] op_sel_hi:[1,0,1]
	v_pk_fma_f32 v[108:109], v[108:109], 0.5, v[114:115] op_sel_hi:[1,0,1]
	v_pk_fma_f32 v[114:115], v[106:107], 0.5, v[136:137] op_sel_hi:[1,0,1]
	v_pk_fma_f32 v[116:117], v[104:105], 0.5, v[118:119] op_sel_hi:[1,0,1]
	v_cvt_pk_bf16_f32 v104, v108, v109
	v_cvt_pk_bf16_f32 v105, v110, v111
	v_pk_fma_f32 v[108:109], v[108:109], v[108:109], 0 op_sel_hi:[1,1,0]
	v_pk_fma_f32 v[110:111], v[110:111], v[110:111], 0 op_sel_hi:[1,1,0]
	v_cvt_pk_bf16_f32 v106, v116, v117
	v_cvt_pk_bf16_f32 v107, v114, v115
	v_pk_fma_f32 v[108:109], v[116:117], v[116:117], v[108:109]
	v_pk_fma_f32 v[110:111], v[114:115], v[114:115], v[110:111]
	v_lshlrev_b32_e32 v114, 16, v176
	v_and_b32_e32 v115, 0xffff0000, v176
	v_lshlrev_b32_e32 v116, 16, v177
	v_and_b32_e32 v117, 0xffff0000, v177
	v_lshlrev_b32_e32 v118, 16, v178
	v_and_b32_e32 v119, 0xffff0000, v178
	v_lshlrev_b32_e32 v136, 16, v179
	v_and_b32_e32 v137, 0xffff0000, v179
	v_pk_fma_f32 v[102:103], v[102:103], 0.5, v[116:117] op_sel_hi:[1,0,1]
	v_pk_fma_f32 v[100:101], v[100:101], 0.5, v[114:115] op_sel_hi:[1,0,1]
	v_pk_fma_f32 v[114:115], v[98:99], 0.5, v[136:137] op_sel_hi:[1,0,1]
	v_pk_fma_f32 v[116:117], v[96:97], 0.5, v[118:119] op_sel_hi:[1,0,1]
	v_pk_fma_f32 v[96:97], v[100:101], v[100:101], v[108:109]
	v_pk_fma_f32 v[98:99], v[102:103], v[102:103], v[110:111]
	v_pk_fma_f32 v[96:97], v[116:117], v[116:117], v[96:97]
	v_pk_fma_f32 v[98:99], v[114:115], v[114:115], v[98:99]
	v_add_f32_e32 v96, v96, v97
	v_add_f32_e32 v97, v98, v99
	v_add_f32_e32 v99, v96, v97
	v_mov_b32_e32 v110, v99
	s_nop 1
	v_permlane16_swap_b32 v110, v99
	v_lshl_add_u64 v[96:97], s[12:13], 0, v[232:233]
	v_lshl_add_u64 v[108:109], v[204:205], 1, v[96:97]
	global_store_dwordx4 v[108:109], v[104:107], off
	v_cvt_pk_bf16_f32 v98, v100, v101
	s_waitcnt lgkmcnt(0)
	v_add_f32_e32 v96, v99, v110
	v_mov_b32_e32 v97, v96
	s_nop 1
	v_permlane32_swap_b32 v97, v96
	v_cvt_pk_bf16_f32 v99, v102, v103
	v_cvt_pk_bf16_f32 v100, v116, v117
	v_cvt_pk_bf16_f32 v101, v114, v115
	global_store_dwordx4 v[108:109], v[98:101], off offset:256
	s_and_saveexec_b64 s[52:53], s[6:7]
	s_cbranch_execz .LBB0_279
	v_lshlrev_b64 v[98:99], 6, v[230:231]
	v_lshl_add_u64 v[98:99], s[70:71], 0, v[98:99]
	v_lshl_add_u64 v[98:99], s[86:87], 2, v[98:99]
	s_lshl_b32 s76, s20, 2
	v_lshl_add_u64 v[98:99], v[98:99], 0, s[76:77]
	s_waitcnt lgkmcnt(0)
	v_add_f32_e32 v96, v96, v97
	global_store_dword v[98:99], v96, off
.LBB0_279:
	s_or_b64 exec, exec, s[52:53]
	v_lshlrev_b32_e32 v96, 16, v172
	s_waitcnt lgkmcnt(0)
	v_and_b32_e32 v97, 0xffff0000, v172
	v_lshlrev_b32_e32 v98, 16, v173
	v_and_b32_e32 v99, 0xffff0000, v173
	v_lshlrev_b32_e32 v100, 16, v174
	v_and_b32_e32 v101, 0xffff0000, v174
	v_lshlrev_b32_e32 v102, 16, v175
	v_and_b32_e32 v103, 0xffff0000, v175
	v_pk_fma_f32 v[94:95], v[94:95], 0.5, v[98:99] op_sel_hi:[1,0,1]
	v_pk_fma_f32 v[92:93], v[92:93], 0.5, v[96:97] op_sel_hi:[1,0,1]
	v_pk_fma_f32 v[96:97], v[90:91], 0.5, v[102:103] op_sel_hi:[1,0,1]
	v_pk_fma_f32 v[98:99], v[88:89], 0.5, v[100:101] op_sel_hi:[1,0,1]
	v_cvt_pk_bf16_f32 v88, v92, v93
	v_cvt_pk_bf16_f32 v89, v94, v95
	v_pk_fma_f32 v[92:93], v[92:93], v[92:93], 0 op_sel_hi:[1,1,0]
	v_pk_fma_f32 v[94:95], v[94:95], v[94:95], 0 op_sel_hi:[1,1,0]
	v_cvt_pk_bf16_f32 v90, v98, v99
	v_cvt_pk_bf16_f32 v91, v96, v97
	v_pk_fma_f32 v[92:93], v[98:99], v[98:99], v[92:93]
	v_pk_fma_f32 v[94:95], v[96:97], v[96:97], v[94:95]
	v_lshlrev_b32_e32 v96, 16, v168
	v_and_b32_e32 v97, 0xffff0000, v168
	v_lshlrev_b32_e32 v98, 16, v169
	v_and_b32_e32 v99, 0xffff0000, v169
	v_lshlrev_b32_e32 v100, 16, v170
	v_and_b32_e32 v101, 0xffff0000, v170
	v_lshlrev_b32_e32 v102, 16, v171
	v_and_b32_e32 v103, 0xffff0000, v171
	v_pk_fma_f32 v[86:87], v[86:87], 0.5, v[98:99] op_sel_hi:[1,0,1]
	v_pk_fma_f32 v[84:85], v[84:85], 0.5, v[96:97] op_sel_hi:[1,0,1]
	v_pk_fma_f32 v[96:97], v[82:83], 0.5, v[102:103] op_sel_hi:[1,0,1]
	v_pk_fma_f32 v[98:99], v[80:81], 0.5, v[100:101] op_sel_hi:[1,0,1]
	v_pk_fma_f32 v[80:81], v[84:85], v[84:85], v[92:93]
	v_pk_fma_f32 v[82:83], v[86:87], v[86:87], v[94:95]
	v_pk_fma_f32 v[80:81], v[98:99], v[98:99], v[80:81]
	v_pk_fma_f32 v[82:83], v[96:97], v[96:97], v[82:83]
	v_add_f32_e32 v80, v80, v81
	v_add_f32_e32 v81, v82, v83
	v_add_f32_e32 v83, v80, v81
	v_mov_b32_e32 v94, v83
	s_nop 1
	v_permlane16_swap_b32 v94, v83
	v_lshl_add_u64 v[80:81], s[12:13], 0, v[228:229]
	v_lshl_add_u64 v[92:93], v[204:205], 1, v[80:81]
	global_store_dwordx4 v[92:93], v[88:91], off
	v_cvt_pk_bf16_f32 v82, v84, v85
	s_waitcnt lgkmcnt(0)
	v_add_f32_e32 v80, v83, v94
	v_mov_b32_e32 v81, v80
	s_nop 1
	v_permlane32_swap_b32 v81, v80
	v_cvt_pk_bf16_f32 v83, v86, v87
	v_cvt_pk_bf16_f32 v84, v98, v99
	v_cvt_pk_bf16_f32 v85, v96, v97
	global_store_dwordx4 v[92:93], v[82:85], off offset:256
	s_and_saveexec_b64 s[52:53], s[6:7]
	s_cbranch_execz .LBB0_281
	v_lshlrev_b64 v[82:83], 6, v[226:227]
	v_lshl_add_u64 v[82:83], s[70:71], 0, v[82:83]
	v_lshl_add_u64 v[82:83], s[86:87], 2, v[82:83]
	s_lshl_b32 s76, s20, 2
	v_lshl_add_u64 v[82:83], v[82:83], 0, s[76:77]
	s_waitcnt lgkmcnt(0)
	v_add_f32_e32 v80, v80, v81
	global_store_dword v[82:83], v80, off
.LBB0_281:
	s_or_b64 exec, exec, s[52:53]
	v_lshlrev_b32_e32 v80, 16, v164
	s_waitcnt lgkmcnt(0)
	v_and_b32_e32 v81, 0xffff0000, v164
	v_lshlrev_b32_e32 v82, 16, v165
	v_and_b32_e32 v83, 0xffff0000, v165
	v_lshlrev_b32_e32 v84, 16, v166
	v_and_b32_e32 v85, 0xffff0000, v166
	v_lshlrev_b32_e32 v86, 16, v167
	v_and_b32_e32 v87, 0xffff0000, v167
	v_pk_fma_f32 v[78:79], v[78:79], 0.5, v[82:83] op_sel_hi:[1,0,1]
	v_pk_fma_f32 v[76:77], v[76:77], 0.5, v[80:81] op_sel_hi:[1,0,1]
	v_pk_fma_f32 v[80:81], v[74:75], 0.5, v[86:87] op_sel_hi:[1,0,1]
	v_pk_fma_f32 v[82:83], v[72:73], 0.5, v[84:85] op_sel_hi:[1,0,1]
	v_cvt_pk_bf16_f32 v72, v76, v77
	v_cvt_pk_bf16_f32 v73, v78, v79
	v_pk_fma_f32 v[76:77], v[76:77], v[76:77], 0 op_sel_hi:[1,1,0]
	v_pk_fma_f32 v[78:79], v[78:79], v[78:79], 0 op_sel_hi:[1,1,0]
	v_cvt_pk_bf16_f32 v74, v82, v83
	v_cvt_pk_bf16_f32 v75, v80, v81
	v_pk_fma_f32 v[76:77], v[82:83], v[82:83], v[76:77]
	v_pk_fma_f32 v[78:79], v[80:81], v[80:81], v[78:79]
	v_lshlrev_b32_e32 v80, 16, v160
	v_and_b32_e32 v81, 0xffff0000, v160
	v_lshlrev_b32_e32 v82, 16, v161
	v_and_b32_e32 v83, 0xffff0000, v161
	v_lshlrev_b32_e32 v84, 16, v162
	v_and_b32_e32 v85, 0xffff0000, v162
	v_lshlrev_b32_e32 v86, 16, v163
	v_and_b32_e32 v87, 0xffff0000, v163
	v_pk_fma_f32 v[70:71], v[70:71], 0.5, v[82:83] op_sel_hi:[1,0,1]
	v_pk_fma_f32 v[68:69], v[68:69], 0.5, v[80:81] op_sel_hi:[1,0,1]
	v_pk_fma_f32 v[80:81], v[66:67], 0.5, v[86:87] op_sel_hi:[1,0,1]
	v_pk_fma_f32 v[82:83], v[64:65], 0.5, v[84:85] op_sel_hi:[1,0,1]
	v_pk_fma_f32 v[64:65], v[68:69], v[68:69], v[76:77]
	v_pk_fma_f32 v[66:67], v[70:71], v[70:71], v[78:79]
	v_pk_fma_f32 v[64:65], v[82:83], v[82:83], v[64:65]
	v_pk_fma_f32 v[66:67], v[80:81], v[80:81], v[66:67]
	v_add_f32_e32 v64, v64, v65
	v_add_f32_e32 v65, v66, v67
	v_add_f32_e32 v67, v64, v65
	v_mov_b32_e32 v78, v67
	s_nop 1
	v_permlane16_swap_b32 v78, v67
	v_lshl_add_u64 v[64:65], s[12:13], 0, v[224:225]
	v_lshl_add_u64 v[76:77], v[204:205], 1, v[64:65]
	global_store_dwordx4 v[76:77], v[72:75], off
	v_cvt_pk_bf16_f32 v66, v68, v69
	s_waitcnt lgkmcnt(0)
	v_add_f32_e32 v64, v67, v78
	v_mov_b32_e32 v65, v64
	s_nop 1
	v_permlane32_swap_b32 v65, v64
	v_cvt_pk_bf16_f32 v67, v70, v71
	v_cvt_pk_bf16_f32 v68, v82, v83
	v_cvt_pk_bf16_f32 v69, v80, v81
	global_store_dwordx4 v[76:77], v[66:69], off offset:256
	s_and_saveexec_b64 s[52:53], s[6:7]
	s_cbranch_execz .LBB0_283
	v_lshlrev_b64 v[66:67], 6, v[222:223]
	v_lshl_add_u64 v[66:67], s[70:71], 0, v[66:67]
	v_lshl_add_u64 v[66:67], s[86:87], 2, v[66:67]
	s_lshl_b32 s76, s20, 2
	v_lshl_add_u64 v[66:67], v[66:67], 0, s[76:77]
	s_waitcnt lgkmcnt(0)
	v_add_f32_e32 v64, v64, v65
	global_store_dword v[66:67], v64, off
.LBB0_283:
	s_or_b64 exec, exec, s[52:53]
	v_lshlrev_b32_e32 v64, 16, v156
	s_waitcnt lgkmcnt(0)
	v_and_b32_e32 v65, 0xffff0000, v156
	v_lshlrev_b32_e32 v66, 16, v157
	v_and_b32_e32 v67, 0xffff0000, v157
	v_lshlrev_b32_e32 v68, 16, v158
	v_and_b32_e32 v69, 0xffff0000, v158
	v_lshlrev_b32_e32 v70, 16, v159
	v_and_b32_e32 v71, 0xffff0000, v159
	v_pk_fma_f32 v[62:63], v[62:63], 0.5, v[66:67] op_sel_hi:[1,0,1]
	v_pk_fma_f32 v[60:61], v[60:61], 0.5, v[64:65] op_sel_hi:[1,0,1]
	v_pk_fma_f32 v[64:65], v[58:59], 0.5, v[70:71] op_sel_hi:[1,0,1]
	v_pk_fma_f32 v[66:67], v[56:57], 0.5, v[68:69] op_sel_hi:[1,0,1]
	v_cvt_pk_bf16_f32 v56, v60, v61
	v_cvt_pk_bf16_f32 v57, v62, v63
	v_pk_fma_f32 v[60:61], v[60:61], v[60:61], 0 op_sel_hi:[1,1,0]
	v_pk_fma_f32 v[62:63], v[62:63], v[62:63], 0 op_sel_hi:[1,1,0]
	v_cvt_pk_bf16_f32 v58, v66, v67
	v_cvt_pk_bf16_f32 v59, v64, v65
	v_pk_fma_f32 v[60:61], v[66:67], v[66:67], v[60:61]
	v_pk_fma_f32 v[62:63], v[64:65], v[64:65], v[62:63]
	v_lshlrev_b32_e32 v64, 16, v152
	v_and_b32_e32 v65, 0xffff0000, v152
	v_lshlrev_b32_e32 v66, 16, v153
	v_and_b32_e32 v67, 0xffff0000, v153
	v_lshlrev_b32_e32 v68, 16, v154
	v_and_b32_e32 v69, 0xffff0000, v154
	v_lshlrev_b32_e32 v70, 16, v155
	v_and_b32_e32 v71, 0xffff0000, v155
	v_pk_fma_f32 v[54:55], v[54:55], 0.5, v[66:67] op_sel_hi:[1,0,1]
	v_pk_fma_f32 v[52:53], v[52:53], 0.5, v[64:65] op_sel_hi:[1,0,1]
	v_pk_fma_f32 v[64:65], v[50:51], 0.5, v[70:71] op_sel_hi:[1,0,1]
	v_pk_fma_f32 v[66:67], v[48:49], 0.5, v[68:69] op_sel_hi:[1,0,1]
	v_pk_fma_f32 v[48:49], v[52:53], v[52:53], v[60:61]
	v_pk_fma_f32 v[50:51], v[54:55], v[54:55], v[62:63]
	v_pk_fma_f32 v[48:49], v[66:67], v[66:67], v[48:49]
	v_pk_fma_f32 v[50:51], v[64:65], v[64:65], v[50:51]
	v_add_f32_e32 v48, v48, v49
	v_add_f32_e32 v49, v50, v51
	v_add_f32_e32 v51, v48, v49
	v_mov_b32_e32 v62, v51
	s_nop 1
	v_permlane16_swap_b32 v62, v51
	v_lshl_add_u64 v[48:49], s[12:13], 0, v[220:221]
	v_lshl_add_u64 v[60:61], v[204:205], 1, v[48:49]
	global_store_dwordx4 v[60:61], v[56:59], off
	v_cvt_pk_bf16_f32 v50, v52, v53
	s_waitcnt lgkmcnt(0)
	v_add_f32_e32 v48, v51, v62
	v_mov_b32_e32 v49, v48
	s_nop 1
	v_permlane32_swap_b32 v49, v48
	v_cvt_pk_bf16_f32 v51, v54, v55
	v_cvt_pk_bf16_f32 v52, v66, v67
	v_cvt_pk_bf16_f32 v53, v64, v65
	global_store_dwordx4 v[60:61], v[50:53], off offset:256
	s_and_saveexec_b64 s[52:53], s[6:7]
	s_cbranch_execz .LBB0_285
	v_lshlrev_b64 v[50:51], 6, v[218:219]
	v_lshl_add_u64 v[50:51], s[70:71], 0, v[50:51]
	v_lshl_add_u64 v[50:51], s[86:87], 2, v[50:51]
	s_lshl_b32 s76, s20, 2
	v_lshl_add_u64 v[50:51], v[50:51], 0, s[76:77]
	s_waitcnt lgkmcnt(0)
	v_add_f32_e32 v48, v48, v49
	global_store_dword v[50:51], v48, off
.LBB0_285:
	s_or_b64 exec, exec, s[52:53]
	v_lshlrev_b32_e32 v48, 16, v148
	s_waitcnt lgkmcnt(0)
	v_and_b32_e32 v49, 0xffff0000, v148
	v_lshlrev_b32_e32 v50, 16, v149
	v_and_b32_e32 v51, 0xffff0000, v149
	v_lshlrev_b32_e32 v52, 16, v150
	v_and_b32_e32 v53, 0xffff0000, v150
	v_lshlrev_b32_e32 v54, 16, v151
	v_and_b32_e32 v55, 0xffff0000, v151
	v_pk_fma_f32 v[46:47], v[46:47], 0.5, v[50:51] op_sel_hi:[1,0,1]
	v_pk_fma_f32 v[44:45], v[44:45], 0.5, v[48:49] op_sel_hi:[1,0,1]
	v_pk_fma_f32 v[48:49], v[42:43], 0.5, v[54:55] op_sel_hi:[1,0,1]
	v_pk_fma_f32 v[50:51], v[40:41], 0.5, v[52:53] op_sel_hi:[1,0,1]
	v_cvt_pk_bf16_f32 v40, v44, v45
	v_cvt_pk_bf16_f32 v41, v46, v47
	v_pk_fma_f32 v[44:45], v[44:45], v[44:45], 0 op_sel_hi:[1,1,0]
	v_pk_fma_f32 v[46:47], v[46:47], v[46:47], 0 op_sel_hi:[1,1,0]
	v_cvt_pk_bf16_f32 v42, v50, v51
	v_cvt_pk_bf16_f32 v43, v48, v49
	v_pk_fma_f32 v[44:45], v[50:51], v[50:51], v[44:45]
	v_pk_fma_f32 v[46:47], v[48:49], v[48:49], v[46:47]
	v_lshlrev_b32_e32 v48, 16, v144
	v_and_b32_e32 v49, 0xffff0000, v144
	v_lshlrev_b32_e32 v50, 16, v145
	v_and_b32_e32 v51, 0xffff0000, v145
	v_lshlrev_b32_e32 v52, 16, v146
	v_and_b32_e32 v53, 0xffff0000, v146
	v_lshlrev_b32_e32 v54, 16, v147
	v_and_b32_e32 v55, 0xffff0000, v147
	v_pk_fma_f32 v[38:39], v[38:39], 0.5, v[50:51] op_sel_hi:[1,0,1]
	v_pk_fma_f32 v[36:37], v[36:37], 0.5, v[48:49] op_sel_hi:[1,0,1]
	v_pk_fma_f32 v[48:49], v[34:35], 0.5, v[54:55] op_sel_hi:[1,0,1]
	v_pk_fma_f32 v[50:51], v[32:33], 0.5, v[52:53] op_sel_hi:[1,0,1]
	v_pk_fma_f32 v[32:33], v[36:37], v[36:37], v[44:45]
	v_pk_fma_f32 v[34:35], v[38:39], v[38:39], v[46:47]
	v_pk_fma_f32 v[32:33], v[50:51], v[50:51], v[32:33]
	v_pk_fma_f32 v[34:35], v[48:49], v[48:49], v[34:35]
	v_add_f32_e32 v32, v32, v33
	v_add_f32_e32 v33, v34, v35
	v_add_f32_e32 v35, v32, v33
	v_mov_b32_e32 v46, v35
	s_nop 1
	v_permlane16_swap_b32 v46, v35
	v_lshl_add_u64 v[32:33], s[12:13], 0, v[216:217]
	v_lshl_add_u64 v[44:45], v[204:205], 1, v[32:33]
	global_store_dwordx4 v[44:45], v[40:43], off
	v_cvt_pk_bf16_f32 v34, v36, v37
	s_waitcnt lgkmcnt(0)
	v_add_f32_e32 v32, v35, v46
	v_mov_b32_e32 v33, v32
	s_nop 1
	v_permlane32_swap_b32 v33, v32
	v_cvt_pk_bf16_f32 v35, v38, v39
	v_cvt_pk_bf16_f32 v36, v50, v51
	v_cvt_pk_bf16_f32 v37, v48, v49
	global_store_dwordx4 v[44:45], v[34:37], off offset:256
	s_and_saveexec_b64 s[52:53], s[6:7]
	s_cbranch_execz .LBB0_287
	v_lshlrev_b64 v[34:35], 6, v[214:215]
	v_lshl_add_u64 v[34:35], s[70:71], 0, v[34:35]
	v_lshl_add_u64 v[34:35], s[86:87], 2, v[34:35]
	s_lshl_b32 s76, s20, 2
	v_lshl_add_u64 v[34:35], v[34:35], 0, s[76:77]
	s_waitcnt lgkmcnt(0)
	v_add_f32_e32 v32, v32, v33
	global_store_dword v[34:35], v32, off
.LBB0_287:
	s_or_b64 exec, exec, s[52:53]
	v_lshlrev_b32_e32 v32, 16, v128
	s_waitcnt lgkmcnt(0)
	v_and_b32_e32 v33, 0xffff0000, v128
	v_lshlrev_b32_e32 v34, 16, v129
	v_and_b32_e32 v35, 0xffff0000, v129
	v_lshlrev_b32_e32 v36, 16, v130
	v_and_b32_e32 v37, 0xffff0000, v130
	v_lshlrev_b32_e32 v38, 16, v131
	v_and_b32_e32 v39, 0xffff0000, v131
	v_pk_fma_f32 v[30:31], v[30:31], 0.5, v[34:35] op_sel_hi:[1,0,1]
	v_pk_fma_f32 v[28:29], v[28:29], 0.5, v[32:33] op_sel_hi:[1,0,1]
	v_pk_fma_f32 v[32:33], v[26:27], 0.5, v[38:39] op_sel_hi:[1,0,1]
	v_pk_fma_f32 v[34:35], v[24:25], 0.5, v[36:37] op_sel_hi:[1,0,1]
	v_cvt_pk_bf16_f32 v24, v28, v29
	v_cvt_pk_bf16_f32 v25, v30, v31
	v_pk_fma_f32 v[28:29], v[28:29], v[28:29], 0 op_sel_hi:[1,1,0]
	v_pk_fma_f32 v[30:31], v[30:31], v[30:31], 0 op_sel_hi:[1,1,0]
	v_cvt_pk_bf16_f32 v26, v34, v35
	v_cvt_pk_bf16_f32 v27, v32, v33
	v_pk_fma_f32 v[28:29], v[34:35], v[34:35], v[28:29]
	v_pk_fma_f32 v[30:31], v[32:33], v[32:33], v[30:31]
	v_lshlrev_b32_e32 v32, 16, v120
	v_and_b32_e32 v33, 0xffff0000, v120
	v_lshlrev_b32_e32 v34, 16, v121
	v_and_b32_e32 v35, 0xffff0000, v121
	v_lshlrev_b32_e32 v36, 16, v122
	v_and_b32_e32 v37, 0xffff0000, v122
	v_lshlrev_b32_e32 v38, 16, v123
	v_and_b32_e32 v39, 0xffff0000, v123
	v_pk_fma_f32 v[22:23], v[22:23], 0.5, v[34:35] op_sel_hi:[1,0,1]
	v_pk_fma_f32 v[20:21], v[20:21], 0.5, v[32:33] op_sel_hi:[1,0,1]
	v_pk_fma_f32 v[32:33], v[18:19], 0.5, v[38:39] op_sel_hi:[1,0,1]
	v_pk_fma_f32 v[34:35], v[16:17], 0.5, v[36:37] op_sel_hi:[1,0,1]
	v_pk_fma_f32 v[16:17], v[20:21], v[20:21], v[28:29]
	v_pk_fma_f32 v[18:19], v[22:23], v[22:23], v[30:31]
	v_pk_fma_f32 v[16:17], v[34:35], v[34:35], v[16:17]
	v_pk_fma_f32 v[18:19], v[32:33], v[32:33], v[18:19]
	v_add_f32_e32 v16, v16, v17
	v_add_f32_e32 v17, v18, v19
	v_add_f32_e32 v19, v16, v17
	v_mov_b32_e32 v30, v19
	s_nop 1
	v_permlane16_swap_b32 v30, v19
	v_lshl_add_u64 v[16:17], s[12:13], 0, v[212:213]
	v_lshl_add_u64 v[28:29], v[204:205], 1, v[16:17]
	global_store_dwordx4 v[28:29], v[24:27], off
	v_cvt_pk_bf16_f32 v18, v20, v21
	s_waitcnt lgkmcnt(0)
	v_add_f32_e32 v16, v19, v30
	v_mov_b32_e32 v17, v16
	s_nop 1
	v_permlane32_swap_b32 v17, v16
	v_cvt_pk_bf16_f32 v19, v22, v23
	v_cvt_pk_bf16_f32 v20, v34, v35
	v_cvt_pk_bf16_f32 v21, v32, v33
	global_store_dwordx4 v[28:29], v[18:21], off offset:256
	s_and_saveexec_b64 s[52:53], s[6:7]
	s_cbranch_execz .LBB0_289
	v_lshlrev_b64 v[18:19], 6, v[210:211]
	v_lshl_add_u64 v[18:19], s[70:71], 0, v[18:19]
	v_lshl_add_u64 v[18:19], s[86:87], 2, v[18:19]
	s_lshl_b32 s76, s20, 2
	v_lshl_add_u64 v[18:19], v[18:19], 0, s[76:77]
	s_waitcnt lgkmcnt(0)
	v_add_f32_e32 v16, v16, v17
	global_store_dword v[18:19], v16, off
.LBB0_289:
	s_or_b64 exec, exec, s[52:53]
	v_lshlrev_b32_e32 v16, 16, v132
	s_waitcnt lgkmcnt(0)
	v_and_b32_e32 v17, 0xffff0000, v132
	v_lshlrev_b32_e32 v18, 16, v133
	v_and_b32_e32 v19, 0xffff0000, v133
	v_lshlrev_b32_e32 v20, 16, v134
	v_and_b32_e32 v21, 0xffff0000, v134
	v_lshlrev_b32_e32 v22, 16, v135
	v_and_b32_e32 v23, 0xffff0000, v135
	v_pk_fma_f32 v[14:15], v[14:15], 0.5, v[18:19] op_sel_hi:[1,0,1]
	v_pk_fma_f32 v[12:13], v[12:13], 0.5, v[16:17] op_sel_hi:[1,0,1]
	v_pk_fma_f32 v[16:17], v[10:11], 0.5, v[22:23] op_sel_hi:[1,0,1]
	v_pk_fma_f32 v[18:19], v[8:9], 0.5, v[20:21] op_sel_hi:[1,0,1]
	v_cvt_pk_bf16_f32 v8, v12, v13
	v_cvt_pk_bf16_f32 v9, v14, v15
	v_pk_fma_f32 v[12:13], v[12:13], v[12:13], 0 op_sel_hi:[1,1,0]
	v_pk_fma_f32 v[14:15], v[14:15], v[14:15], 0 op_sel_hi:[1,1,0]
	v_cvt_pk_bf16_f32 v10, v18, v19
	v_cvt_pk_bf16_f32 v11, v16, v17
	v_pk_fma_f32 v[12:13], v[18:19], v[18:19], v[12:13]
	v_pk_fma_f32 v[14:15], v[16:17], v[16:17], v[14:15]
	v_lshlrev_b32_e32 v16, 16, v124
	v_and_b32_e32 v17, 0xffff0000, v124
	v_lshlrev_b32_e32 v18, 16, v125
	v_and_b32_e32 v19, 0xffff0000, v125
	v_lshlrev_b32_e32 v20, 16, v126
	v_and_b32_e32 v21, 0xffff0000, v126
	v_lshlrev_b32_e32 v22, 16, v127
	v_and_b32_e32 v23, 0xffff0000, v127
	v_pk_fma_f32 v[6:7], v[6:7], 0.5, v[18:19] op_sel_hi:[1,0,1]
	v_pk_fma_f32 v[4:5], v[4:5], 0.5, v[16:17] op_sel_hi:[1,0,1]
	v_pk_fma_f32 v[16:17], v[2:3], 0.5, v[22:23] op_sel_hi:[1,0,1]
	v_pk_fma_f32 v[18:19], v[0:1], 0.5, v[20:21] op_sel_hi:[1,0,1]
	v_pk_fma_f32 v[0:1], v[4:5], v[4:5], v[12:13]
	v_pk_fma_f32 v[2:3], v[6:7], v[6:7], v[14:15]
	v_pk_fma_f32 v[0:1], v[18:19], v[18:19], v[0:1]
	v_pk_fma_f32 v[2:3], v[16:17], v[16:17], v[2:3]
	v_add_f32_e32 v0, v0, v1
	v_add_f32_e32 v1, v2, v3
	v_add_f32_e32 v3, v0, v1
	v_mov_b32_e32 v14, v3
	s_nop 1
	v_permlane16_swap_b32 v14, v3
	v_lshl_add_u64 v[0:1], s[12:13], 0, v[208:209]
	v_lshl_add_u64 v[12:13], v[204:205], 1, v[0:1]
	global_store_dwordx4 v[12:13], v[8:11], off
	v_cvt_pk_bf16_f32 v2, v4, v5
	s_waitcnt lgkmcnt(0)
	v_add_f32_e32 v0, v3, v14
	v_mov_b32_e32 v1, v0
	s_nop 1
	v_permlane32_swap_b32 v1, v0
	v_cvt_pk_bf16_f32 v3, v6, v7
	v_cvt_pk_bf16_f32 v4, v18, v19
	v_cvt_pk_bf16_f32 v5, v16, v17
	global_store_dwordx4 v[12:13], v[2:5], off offset:256
	s_and_saveexec_b64 s[52:53], s[6:7]
	s_cbranch_execz .LBB0_291
	v_lshlrev_b64 v[2:3], 6, v[206:207]
	v_lshl_add_u64 v[2:3], s[70:71], 0, v[2:3]
	v_lshl_add_u64 v[2:3], s[86:87], 2, v[2:3]
	s_lshl_b32 s76, s20, 2
	v_lshl_add_u64 v[2:3], v[2:3], 0, s[76:77]
	s_waitcnt lgkmcnt(0)
	v_add_f32_e32 v0, v0, v1
	global_store_dword v[2:3], v0, off

.LBB0_996:
	v_lshl_or_b32 v204, s10, 8, v244
	v_lshl_add_u32 v234, s80, 8, v242
	v_ashrrev_i32_e32 v205, 31, v204
	v_lshlrev_b64 v[236:237], 1, v[204:205]
	v_ashrrev_i32_e32 v235, 31, v234
	v_lshl_add_u64 v[124:125], s[12:13], 0, v[236:237]
	v_lshlrev_b64 v[238:239], 11, v[234:235]
	v_lshl_add_u64 v[120:121], v[124:125], 0, v[238:239]
	global_load_dwordx4 v[188:191], v[120:121], off
	global_load_dwordx4 v[184:187], v[120:121], off offset:256
	v_or_b32_e32 v230, 16, v234
	v_ashrrev_i32_e32 v231, 31, v230
	v_or_b32_e32 v226, 32, v234
	v_lshlrev_b64 v[232:233], 11, v[230:231]
	v_ashrrev_i32_e32 v227, 31, v226
	v_or_b32_e32 v222, 48, v234
	v_lshl_add_u64 v[120:121], v[124:125], 0, v[232:233]
	v_lshlrev_b64 v[228:229], 11, v[226:227]
	v_ashrrev_i32_e32 v223, 31, v222
	v_add_u32_e32 v218, 0x80, v234
	global_load_dwordx4 v[180:183], v[120:121], off
	global_load_dwordx4 v[176:179], v[120:121], off offset:256
	v_lshl_add_u64 v[120:121], v[124:125], 0, v[228:229]
	v_lshlrev_b64 v[224:225], 11, v[222:223]
	v_ashrrev_i32_e32 v219, 31, v218
	v_add_u32_e32 v214, 0x90, v234
	global_load_dwordx4 v[172:175], v[120:121], off
	global_load_dwordx4 v[168:171], v[120:121], off offset:256
	v_lshl_add_u64 v[120:121], v[124:125], 0, v[224:225]
	v_lshlrev_b64 v[220:221], 11, v[218:219]
	v_ashrrev_i32_e32 v215, 31, v214
	v_add_u32_e32 v210, 0xa0, v234
	v_add_u32_e32 v206, 0xb0, v234
	global_load_dwordx4 v[164:167], v[120:121], off
	global_load_dwordx4 v[160:163], v[120:121], off offset:256
	v_lshl_add_u64 v[120:121], v[124:125], 0, v[220:221]
	v_lshlrev_b64 v[216:217], 11, v[214:215]
	v_ashrrev_i32_e32 v211, 31, v210
	v_ashrrev_i32_e32 v207, 31, v206
	global_load_dwordx4 v[156:159], v[120:121], off
	global_load_dwordx4 v[152:155], v[120:121], off offset:256
	v_lshl_add_u64 v[120:121], v[124:125], 0, v[216:217]
	v_lshlrev_b64 v[212:213], 11, v[210:211]
	v_lshlrev_b64 v[208:209], 11, v[206:207]
	global_load_dwordx4 v[148:151], v[120:121], off
	global_load_dwordx4 v[144:147], v[120:121], off offset:256
	v_lshl_add_u64 v[120:121], v[124:125], 0, v[212:213]
	v_lshl_add_u64 v[124:125], v[124:125], 0, v[208:209]
	global_load_dwordx4 v[128:131], v[120:121], off
	s_nop 0
	global_load_dwordx4 v[120:123], v[120:121], off offset:256
	s_nop 0
	global_load_dwordx4 v[132:135], v[124:125], off
	s_nop 0
	global_load_dwordx4 v[124:127], v[124:125], off offset:256
	v_lshl_add_u64 v[238:239], s[12:13], 0, v[238:239]
	v_lshl_add_u64 v[236:237], v[238:239], 0, v[236:237]
	s_lshl_b32 s80, s10, 2
	s_ashr_i32 s81, s80, 31
	s_waitcnt vmcnt(0)
	v_lshlrev_b32_e32 v250, 16, v188
	v_and_b32_e32 v251, 0xffff0000, v188
	v_lshlrev_b32_e32 v188, 16, v189
	v_and_b32_e32 v189, 0xffff0000, v189
	v_lshlrev_b32_e32 v252, 16, v190
	v_and_b32_e32 v253, 0xffff0000, v190
	v_lshlrev_b32_e32 v190, 16, v191
	v_and_b32_e32 v191, 0xffff0000, v191
	v_pk_add_f32 v[142:143], v[142:143], v[188:189]
	v_pk_add_f32 v[140:141], v[140:141], v[250:251]
	v_pk_add_f32 v[188:189], v[138:139], v[190:191]
	v_pk_add_f32 v[190:191], v[136:137], v[252:253]
	v_cvt_pk_bf16_f32 v136, v140, v141
	v_cvt_pk_bf16_f32 v137, v142, v143
	s_nop 0
	v_cvt_pk_bf16_f32 v138, v190, v191
	v_cvt_pk_bf16_f32 v139, v188, v189
	global_store_dwordx4 v[236:237], v[136:139], off
	s_nop 1
	v_pk_fma_f32 v[136:137], v[140:141], v[140:141], 0 op_sel_hi:[1,1,0]
	v_pk_fma_f32 v[138:139], v[142:143], v[142:143], 0 op_sel_hi:[1,1,0]
	v_lshlrev_b32_e32 v140, 16, v184
	v_and_b32_e32 v141, 0xffff0000, v184
	v_lshlrev_b32_e32 v142, 16, v185
	v_and_b32_e32 v143, 0xffff0000, v185
	v_lshlrev_b32_e32 v184, 16, v186
	v_and_b32_e32 v185, 0xffff0000, v186
	v_lshlrev_b32_e32 v186, 16, v187
	v_and_b32_e32 v187, 0xffff0000, v187
	v_pk_fma_f32 v[138:139], v[188:189], v[188:189], v[138:139]
	v_pk_fma_f32 v[136:137], v[190:191], v[190:191], v[136:137]
	v_pk_add_f32 v[118:119], v[118:119], v[142:143]
	v_pk_add_f32 v[116:117], v[116:117], v[140:141]
	v_pk_add_f32 v[140:141], v[114:115], v[186:187]
	v_pk_add_f32 v[142:143], v[112:113], v[184:185]
	v_cvt_pk_bf16_f32 v112, v116, v117
	v_cvt_pk_bf16_f32 v113, v118, v119
	s_nop 0
	v_cvt_pk_bf16_f32 v114, v142, v143
	v_cvt_pk_bf16_f32 v115, v140, v141
	global_store_dwordx4 v[236:237], v[112:115], off offset:256
	s_nop 1
	v_pk_fma_f32 v[112:113], v[116:117], v[116:117], v[136:137]
	v_pk_fma_f32 v[114:115], v[118:119], v[118:119], v[138:139]
	v_pk_fma_f32 v[112:113], v[142:143], v[142:143], v[112:113]
	v_pk_fma_f32 v[114:115], v[140:141], v[140:141], v[114:115]
	v_add_f32_e32 v112, v112, v113
	v_add_f32_e32 v113, v114, v115
	v_and_b32_e32 v114, 64, v248
	v_add_f32_e32 v113, v112, v113
	v_xor_b32_e32 v112, 16, v248
	v_add_u32_e32 v115, 64, v114
	v_cmp_lt_i32_e32 vcc, v112, v115
	s_nop 1
	v_cndmask_b32_e32 v112, v248, v112, vcc
	v_lshlrev_b32_e32 v112, 2, v112
	v_mov_b32_e32 v114, v113
	s_nop 1
	v_permlane16_swap_b32 v114, v113
	s_waitcnt lgkmcnt(0)
	v_add_f32_e32 v114, v113, v114
	v_xor_b32_e32 v113, 32, v248
	v_cmp_lt_i32_e32 vcc, v113, v115
	s_nop 1
	v_cndmask_b32_e32 v113, v248, v113, vcc
	v_lshlrev_b32_e32 v113, 2, v113
	v_mov_b32_e32 v115, v114
	s_nop 1
	v_permlane32_swap_b32 v115, v114
	s_and_saveexec_b64 s[54:55], s[4:5]
	s_cbranch_execz .LBB0_998
	v_lshlrev_b64 v[116:117], 6, v[234:235]
	v_lshl_add_u64 v[116:117], s[70:71], 0, v[116:117]
	v_lshl_add_u64 v[116:117], s[80:81], 2, v[116:117]
	s_lshl_b32 s10, s20, 2
	v_lshl_add_u64 v[116:117], v[116:117], 0, s[10:11]
	s_waitcnt lgkmcnt(0)
	v_add_f32_e32 v114, v114, v115
	global_store_dword v[116:117], v114, off
.LBB0_998:
	s_or_b64 exec, exec, s[54:55]
	v_lshlrev_b32_e32 v114, 16, v180
	s_waitcnt lgkmcnt(0)
	v_and_b32_e32 v115, 0xffff0000, v180
	v_lshlrev_b32_e32 v116, 16, v181
	v_and_b32_e32 v117, 0xffff0000, v181
	v_lshlrev_b32_e32 v118, 16, v182
	v_and_b32_e32 v119, 0xffff0000, v182
	v_lshlrev_b32_e32 v136, 16, v183
	v_and_b32_e32 v137, 0xffff0000, v183
	v_pk_add_f32 v[110:111], v[110:111], v[116:117]
	v_pk_add_f32 v[108:109], v[108:109], v[114:115]
	v_pk_add_f32 v[114:115], v[106:107], v[136:137]
	v_pk_add_f32 v[116:117], v[104:105], v[118:119]
	v_cvt_pk_bf16_f32 v104, v108, v109
	v_cvt_pk_bf16_f32 v105, v110, v111
	v_pk_fma_f32 v[108:109], v[108:109], v[108:109], 0 op_sel_hi:[1,1,0]
	v_pk_fma_f32 v[110:111], v[110:111], v[110:111], 0 op_sel_hi:[1,1,0]
	v_cvt_pk_bf16_f32 v106, v116, v117
	v_cvt_pk_bf16_f32 v107, v114, v115
	v_pk_fma_f32 v[108:109], v[116:117], v[116:117], v[108:109]
	v_pk_fma_f32 v[110:111], v[114:115], v[114:115], v[110:111]
	v_lshlrev_b32_e32 v114, 16, v176
	v_and_b32_e32 v115, 0xffff0000, v176
	v_lshlrev_b32_e32 v116, 16, v177
	v_and_b32_e32 v117, 0xffff0000, v177
	v_lshlrev_b32_e32 v118, 16, v178
	v_and_b32_e32 v119, 0xffff0000, v178
	v_lshlrev_b32_e32 v136, 16, v179
	v_and_b32_e32 v137, 0xffff0000, v179
	v_pk_add_f32 v[102:103], v[102:103], v[116:117]
	v_pk_add_f32 v[100:101], v[100:101], v[114:115]
	v_pk_add_f32 v[114:115], v[98:99], v[136:137]
	v_pk_add_f32 v[116:117], v[96:97], v[118:119]
	v_pk_fma_f32 v[96:97], v[100:101], v[100:101], v[108:109]
	v_pk_fma_f32 v[98:99], v[102:103], v[102:103], v[110:111]
	v_pk_fma_f32 v[96:97], v[116:117], v[116:117], v[96:97]
	v_pk_fma_f32 v[98:99], v[114:115], v[114:115], v[98:99]
	v_add_f32_e32 v96, v96, v97
	v_add_f32_e32 v97, v98, v99
	v_add_f32_e32 v99, v96, v97
	v_mov_b32_e32 v110, v99
	s_nop 1
	v_permlane16_swap_b32 v110, v99
	v_lshl_add_u64 v[96:97], s[12:13], 0, v[232:233]
	v_lshl_add_u64 v[108:109], v[204:205], 1, v[96:97]
	global_store_dwordx4 v[108:109], v[104:107], off
	v_cvt_pk_bf16_f32 v98, v100, v101
	s_waitcnt lgkmcnt(0)
	v_add_f32_e32 v96, v99, v110
	v_mov_b32_e32 v97, v96
	s_nop 1
	v_permlane32_swap_b32 v97, v96
	v_cvt_pk_bf16_f32 v99, v102, v103
	v_cvt_pk_bf16_f32 v100, v116, v117
	v_cvt_pk_bf16_f32 v101, v114, v115
	global_store_dwordx4 v[108:109], v[98:101], off offset:256
	s_and_saveexec_b64 s[54:55], s[4:5]
	s_cbranch_execz .LBB0_1000
	v_lshlrev_b64 v[98:99], 6, v[230:231]
	v_lshl_add_u64 v[98:99], s[70:71], 0, v[98:99]
	v_lshl_add_u64 v[98:99], s[80:81], 2, v[98:99]
	s_lshl_b32 s10, s20, 2
	v_lshl_add_u64 v[98:99], v[98:99], 0, s[10:11]
	s_waitcnt lgkmcnt(0)
	v_add_f32_e32 v96, v96, v97
	global_store_dword v[98:99], v96, off
.LBB0_1000:
	s_or_b64 exec, exec, s[54:55]
	v_lshlrev_b32_e32 v96, 16, v172
	s_waitcnt lgkmcnt(0)
	v_and_b32_e32 v97, 0xffff0000, v172
	v_lshlrev_b32_e32 v98, 16, v173
	v_and_b32_e32 v99, 0xffff0000, v173
	v_lshlrev_b32_e32 v100, 16, v174
	v_and_b32_e32 v101, 0xffff0000, v174
	v_lshlrev_b32_e32 v102, 16, v175
	v_and_b32_e32 v103, 0xffff0000, v175
	v_pk_add_f32 v[94:95], v[94:95], v[98:99]
	v_pk_add_f32 v[92:93], v[92:93], v[96:97]
	v_pk_add_f32 v[96:97], v[90:91], v[102:103]
	v_pk_add_f32 v[98:99], v[88:89], v[100:101]
	v_cvt_pk_bf16_f32 v88, v92, v93
	v_cvt_pk_bf16_f32 v89, v94, v95
	v_pk_fma_f32 v[92:93], v[92:93], v[92:93], 0 op_sel_hi:[1,1,0]
	v_pk_fma_f32 v[94:95], v[94:95], v[94:95], 0 op_sel_hi:[1,1,0]
	v_cvt_pk_bf16_f32 v90, v98, v99
	v_cvt_pk_bf16_f32 v91, v96, v97
	v_pk_fma_f32 v[92:93], v[98:99], v[98:99], v[92:93]
	v_pk_fma_f32 v[94:95], v[96:97], v[96:97], v[94:95]
	v_lshlrev_b32_e32 v96, 16, v168
	v_and_b32_e32 v97, 0xffff0000, v168
	v_lshlrev_b32_e32 v98, 16, v169
	v_and_b32_e32 v99, 0xffff0000, v169
	v_lshlrev_b32_e32 v100, 16, v170
	v_and_b32_e32 v101, 0xffff0000, v170
	v_lshlrev_b32_e32 v102, 16, v171
	v_and_b32_e32 v103, 0xffff0000, v171
	v_pk_add_f32 v[86:87], v[86:87], v[98:99]
	v_pk_add_f32 v[84:85], v[84:85], v[96:97]
	v_pk_add_f32 v[96:97], v[82:83], v[102:103]
	v_pk_add_f32 v[98:99], v[80:81], v[100:101]
	v_pk_fma_f32 v[80:81], v[84:85], v[84:85], v[92:93]
	v_pk_fma_f32 v[82:83], v[86:87], v[86:87], v[94:95]
	v_pk_fma_f32 v[80:81], v[98:99], v[98:99], v[80:81]
	v_pk_fma_f32 v[82:83], v[96:97], v[96:97], v[82:83]
	v_add_f32_e32 v80, v80, v81
	v_add_f32_e32 v81, v82, v83
	v_add_f32_e32 v83, v80, v81
	v_mov_b32_e32 v94, v83
	s_nop 1
	v_permlane16_swap_b32 v94, v83
	v_lshl_add_u64 v[80:81], s[12:13], 0, v[228:229]
	v_lshl_add_u64 v[92:93], v[204:205], 1, v[80:81]
	global_store_dwordx4 v[92:93], v[88:91], off
	v_cvt_pk_bf16_f32 v82, v84, v85
	s_waitcnt lgkmcnt(0)
	v_add_f32_e32 v80, v83, v94
	v_mov_b32_e32 v81, v80
	s_nop 1
	v_permlane32_swap_b32 v81, v80
	v_cvt_pk_bf16_f32 v83, v86, v87
	v_cvt_pk_bf16_f32 v84, v98, v99
	v_cvt_pk_bf16_f32 v85, v96, v97
	global_store_dwordx4 v[92:93], v[82:85], off offset:256
	s_and_saveexec_b64 s[54:55], s[4:5]
	s_cbranch_execz .LBB0_1002
	v_lshlrev_b64 v[82:83], 6, v[226:227]
	v_lshl_add_u64 v[82:83], s[70:71], 0, v[82:83]
	v_lshl_add_u64 v[82:83], s[80:81], 2, v[82:83]
	s_lshl_b32 s10, s20, 2
	v_lshl_add_u64 v[82:83], v[82:83], 0, s[10:11]
	s_waitcnt lgkmcnt(0)
	v_add_f32_e32 v80, v80, v81
	global_store_dword v[82:83], v80, off
.LBB0_1002:
	s_or_b64 exec, exec, s[54:55]
	v_lshlrev_b32_e32 v80, 16, v164
	s_waitcnt lgkmcnt(0)
	v_and_b32_e32 v81, 0xffff0000, v164
	v_lshlrev_b32_e32 v82, 16, v165
	v_and_b32_e32 v83, 0xffff0000, v165
	v_lshlrev_b32_e32 v84, 16, v166
	v_and_b32_e32 v85, 0xffff0000, v166
	v_lshlrev_b32_e32 v86, 16, v167
	v_and_b32_e32 v87, 0xffff0000, v167
	v_pk_add_f32 v[78:79], v[78:79], v[82:83]
	v_pk_add_f32 v[76:77], v[76:77], v[80:81]
	v_pk_add_f32 v[80:81], v[74:75], v[86:87]
	v_pk_add_f32 v[82:83], v[72:73], v[84:85]
	v_cvt_pk_bf16_f32 v72, v76, v77
	v_cvt_pk_bf16_f32 v73, v78, v79
	v_pk_fma_f32 v[76:77], v[76:77], v[76:77], 0 op_sel_hi:[1,1,0]
	v_pk_fma_f32 v[78:79], v[78:79], v[78:79], 0 op_sel_hi:[1,1,0]
	v_cvt_pk_bf16_f32 v74, v82, v83
	v_cvt_pk_bf16_f32 v75, v80, v81
	v_pk_fma_f32 v[76:77], v[82:83], v[82:83], v[76:77]
	v_pk_fma_f32 v[78:79], v[80:81], v[80:81], v[78:79]
	v_lshlrev_b32_e32 v80, 16, v160
	v_and_b32_e32 v81, 0xffff0000, v160
	v_lshlrev_b32_e32 v82, 16, v161
	v_and_b32_e32 v83, 0xffff0000, v161
	v_lshlrev_b32_e32 v84, 16, v162
	v_and_b32_e32 v85, 0xffff0000, v162
	v_lshlrev_b32_e32 v86, 16, v163
	v_and_b32_e32 v87, 0xffff0000, v163
	v_pk_add_f32 v[70:71], v[70:71], v[82:83]
	v_pk_add_f32 v[68:69], v[68:69], v[80:81]
	v_pk_add_f32 v[80:81], v[66:67], v[86:87]
	v_pk_add_f32 v[82:83], v[64:65], v[84:85]
	v_pk_fma_f32 v[64:65], v[68:69], v[68:69], v[76:77]
	v_pk_fma_f32 v[66:67], v[70:71], v[70:71], v[78:79]
	v_pk_fma_f32 v[64:65], v[82:83], v[82:83], v[64:65]
	v_pk_fma_f32 v[66:67], v[80:81], v[80:81], v[66:67]
	v_add_f32_e32 v64, v64, v65
	v_add_f32_e32 v65, v66, v67
	v_add_f32_e32 v67, v64, v65
	v_mov_b32_e32 v78, v67
	s_nop 1
	v_permlane16_swap_b32 v78, v67
	v_lshl_add_u64 v[64:65], s[12:13], 0, v[224:225]
	v_lshl_add_u64 v[76:77], v[204:205], 1, v[64:65]
	global_store_dwordx4 v[76:77], v[72:75], off
	v_cvt_pk_bf16_f32 v66, v68, v69
	s_waitcnt lgkmcnt(0)
	v_add_f32_e32 v64, v67, v78
	v_mov_b32_e32 v65, v64
	s_nop 1
	v_permlane32_swap_b32 v65, v64
	v_cvt_pk_bf16_f32 v67, v70, v71
	v_cvt_pk_bf16_f32 v68, v82, v83
	v_cvt_pk_bf16_f32 v69, v80, v81
	global_store_dwordx4 v[76:77], v[66:69], off offset:256
	s_and_saveexec_b64 s[54:55], s[4:5]
	s_cbranch_execz .LBB0_1004
	v_lshlrev_b64 v[66:67], 6, v[222:223]
	v_lshl_add_u64 v[66:67], s[70:71], 0, v[66:67]
	v_lshl_add_u64 v[66:67], s[80:81], 2, v[66:67]
	s_lshl_b32 s10, s20, 2
	v_lshl_add_u64 v[66:67], v[66:67], 0, s[10:11]
	s_waitcnt lgkmcnt(0)
	v_add_f32_e32 v64, v64, v65
	global_store_dword v[66:67], v64, off
.LBB0_1004:
	s_or_b64 exec, exec, s[54:55]
	v_lshlrev_b32_e32 v64, 16, v156
	s_waitcnt lgkmcnt(0)
	v_and_b32_e32 v65, 0xffff0000, v156
	v_lshlrev_b32_e32 v66, 16, v157
	v_and_b32_e32 v67, 0xffff0000, v157
	v_lshlrev_b32_e32 v68, 16, v158
	v_and_b32_e32 v69, 0xffff0000, v158
	v_lshlrev_b32_e32 v70, 16, v159
	v_and_b32_e32 v71, 0xffff0000, v159
	v_pk_add_f32 v[62:63], v[62:63], v[66:67]
	v_pk_add_f32 v[60:61], v[60:61], v[64:65]
	v_pk_add_f32 v[64:65], v[58:59], v[70:71]
	v_pk_add_f32 v[66:67], v[56:57], v[68:69]
	v_cvt_pk_bf16_f32 v56, v60, v61
	v_cvt_pk_bf16_f32 v57, v62, v63
	v_pk_fma_f32 v[60:61], v[60:61], v[60:61], 0 op_sel_hi:[1,1,0]
	v_pk_fma_f32 v[62:63], v[62:63], v[62:63], 0 op_sel_hi:[1,1,0]
	v_cvt_pk_bf16_f32 v58, v66, v67
	v_cvt_pk_bf16_f32 v59, v64, v65
	v_pk_fma_f32 v[60:61], v[66:67], v[66:67], v[60:61]
	v_pk_fma_f32 v[62:63], v[64:65], v[64:65], v[62:63]
	v_lshlrev_b32_e32 v64, 16, v152
	v_and_b32_e32 v65, 0xffff0000, v152
	v_lshlrev_b32_e32 v66, 16, v153
	v_and_b32_e32 v67, 0xffff0000, v153
	v_lshlrev_b32_e32 v68, 16, v154
	v_and_b32_e32 v69, 0xffff0000, v154
	v_lshlrev_b32_e32 v70, 16, v155
	v_and_b32_e32 v71, 0xffff0000, v155
	v_pk_add_f32 v[54:55], v[54:55], v[66:67]
	v_pk_add_f32 v[52:53], v[52:53], v[64:65]
	v_pk_add_f32 v[64:65], v[50:51], v[70:71]
	v_pk_add_f32 v[66:67], v[48:49], v[68:69]
	v_pk_fma_f32 v[48:49], v[52:53], v[52:53], v[60:61]
	v_pk_fma_f32 v[50:51], v[54:55], v[54:55], v[62:63]
	v_pk_fma_f32 v[48:49], v[66:67], v[66:67], v[48:49]
	v_pk_fma_f32 v[50:51], v[64:65], v[64:65], v[50:51]
	v_add_f32_e32 v48, v48, v49
	v_add_f32_e32 v49, v50, v51
	v_add_f32_e32 v51, v48, v49
	v_mov_b32_e32 v62, v51
	s_nop 1
	v_permlane16_swap_b32 v62, v51
	v_lshl_add_u64 v[48:49], s[12:13], 0, v[220:221]
	v_lshl_add_u64 v[60:61], v[204:205], 1, v[48:49]
	global_store_dwordx4 v[60:61], v[56:59], off
	v_cvt_pk_bf16_f32 v50, v52, v53
	s_waitcnt lgkmcnt(0)
	v_add_f32_e32 v48, v51, v62
	v_mov_b32_e32 v49, v48
	s_nop 1
	v_permlane32_swap_b32 v49, v48
	v_cvt_pk_bf16_f32 v51, v54, v55
	v_cvt_pk_bf16_f32 v52, v66, v67
	v_cvt_pk_bf16_f32 v53, v64, v65
	global_store_dwordx4 v[60:61], v[50:53], off offset:256
	s_and_saveexec_b64 s[54:55], s[4:5]
	s_cbranch_execz .LBB0_1006
	v_lshlrev_b64 v[50:51], 6, v[218:219]
	v_lshl_add_u64 v[50:51], s[70:71], 0, v[50:51]
	v_lshl_add_u64 v[50:51], s[80:81], 2, v[50:51]
	s_lshl_b32 s10, s20, 2
	v_lshl_add_u64 v[50:51], v[50:51], 0, s[10:11]
	s_waitcnt lgkmcnt(0)
	v_add_f32_e32 v48, v48, v49
	global_store_dword v[50:51], v48, off
.LBB0_1006:
	s_or_b64 exec, exec, s[54:55]
	v_lshlrev_b32_e32 v48, 16, v148
	s_waitcnt lgkmcnt(0)
	v_and_b32_e32 v49, 0xffff0000, v148
	v_lshlrev_b32_e32 v50, 16, v149
	v_and_b32_e32 v51, 0xffff0000, v149
	v_lshlrev_b32_e32 v52, 16, v150
	v_and_b32_e32 v53, 0xffff0000, v150
	v_lshlrev_b32_e32 v54, 16, v151
	v_and_b32_e32 v55, 0xffff0000, v151
	v_pk_add_f32 v[46:47], v[46:47], v[50:51]
	v_pk_add_f32 v[44:45], v[44:45], v[48:49]
	v_pk_add_f32 v[48:49], v[42:43], v[54:55]
	v_pk_add_f32 v[50:51], v[40:41], v[52:53]
	v_cvt_pk_bf16_f32 v40, v44, v45
	v_cvt_pk_bf16_f32 v41, v46, v47
	v_pk_fma_f32 v[44:45], v[44:45], v[44:45], 0 op_sel_hi:[1,1,0]
	v_pk_fma_f32 v[46:47], v[46:47], v[46:47], 0 op_sel_hi:[1,1,0]
	v_cvt_pk_bf16_f32 v42, v50, v51
	v_cvt_pk_bf16_f32 v43, v48, v49
	v_pk_fma_f32 v[44:45], v[50:51], v[50:51], v[44:45]
	v_pk_fma_f32 v[46:47], v[48:49], v[48:49], v[46:47]
	v_lshlrev_b32_e32 v48, 16, v144
	v_and_b32_e32 v49, 0xffff0000, v144
	v_lshlrev_b32_e32 v50, 16, v145
	v_and_b32_e32 v51, 0xffff0000, v145
	v_lshlrev_b32_e32 v52, 16, v146
	v_and_b32_e32 v53, 0xffff0000, v146
	v_lshlrev_b32_e32 v54, 16, v147
	v_and_b32_e32 v55, 0xffff0000, v147
	v_pk_add_f32 v[38:39], v[38:39], v[50:51]
	v_pk_add_f32 v[36:37], v[36:37], v[48:49]
	v_pk_add_f32 v[48:49], v[34:35], v[54:55]
	v_pk_add_f32 v[50:51], v[32:33], v[52:53]
	v_pk_fma_f32 v[32:33], v[36:37], v[36:37], v[44:45]
	v_pk_fma_f32 v[34:35], v[38:39], v[38:39], v[46:47]
	v_pk_fma_f32 v[32:33], v[50:51], v[50:51], v[32:33]
	v_pk_fma_f32 v[34:35], v[48:49], v[48:49], v[34:35]
	v_add_f32_e32 v32, v32, v33
	v_add_f32_e32 v33, v34, v35
	v_add_f32_e32 v35, v32, v33
	v_mov_b32_e32 v46, v35
	s_nop 1
	v_permlane16_swap_b32 v46, v35
	v_lshl_add_u64 v[32:33], s[12:13], 0, v[216:217]
	v_lshl_add_u64 v[44:45], v[204:205], 1, v[32:33]
	global_store_dwordx4 v[44:45], v[40:43], off
	v_cvt_pk_bf16_f32 v34, v36, v37
	s_waitcnt lgkmcnt(0)
	v_add_f32_e32 v32, v35, v46
	v_mov_b32_e32 v33, v32
	s_nop 1
	v_permlane32_swap_b32 v33, v32
	v_cvt_pk_bf16_f32 v35, v38, v39
	v_cvt_pk_bf16_f32 v36, v50, v51
	v_cvt_pk_bf16_f32 v37, v48, v49
	global_store_dwordx4 v[44:45], v[34:37], off offset:256
	s_and_saveexec_b64 s[54:55], s[4:5]
	s_cbranch_execz .LBB0_1008
	v_lshlrev_b64 v[34:35], 6, v[214:215]
	v_lshl_add_u64 v[34:35], s[70:71], 0, v[34:35]
	v_lshl_add_u64 v[34:35], s[80:81], 2, v[34:35]
	s_lshl_b32 s10, s20, 2
	v_lshl_add_u64 v[34:35], v[34:35], 0, s[10:11]
	s_waitcnt lgkmcnt(0)
	v_add_f32_e32 v32, v32, v33
	global_store_dword v[34:35], v32, off
.LBB0_1008:
	s_or_b64 exec, exec, s[54:55]
	v_lshlrev_b32_e32 v32, 16, v128
	s_waitcnt lgkmcnt(0)
	v_and_b32_e32 v33, 0xffff0000, v128
	v_lshlrev_b32_e32 v34, 16, v129
	v_and_b32_e32 v35, 0xffff0000, v129
	v_lshlrev_b32_e32 v36, 16, v130
	v_and_b32_e32 v37, 0xffff0000, v130
	v_lshlrev_b32_e32 v38, 16, v131
	v_and_b32_e32 v39, 0xffff0000, v131
	v_pk_add_f32 v[30:31], v[30:31], v[34:35]
	v_pk_add_f32 v[28:29], v[28:29], v[32:33]
	v_pk_add_f32 v[32:33], v[26:27], v[38:39]
	v_pk_add_f32 v[34:35], v[24:25], v[36:37]
	v_cvt_pk_bf16_f32 v24, v28, v29
	v_cvt_pk_bf16_f32 v25, v30, v31
	v_pk_fma_f32 v[28:29], v[28:29], v[28:29], 0 op_sel_hi:[1,1,0]
	v_pk_fma_f32 v[30:31], v[30:31], v[30:31], 0 op_sel_hi:[1,1,0]
	v_cvt_pk_bf16_f32 v26, v34, v35
	v_cvt_pk_bf16_f32 v27, v32, v33
	v_pk_fma_f32 v[28:29], v[34:35], v[34:35], v[28:29]
	v_pk_fma_f32 v[30:31], v[32:33], v[32:33], v[30:31]
	v_lshlrev_b32_e32 v32, 16, v120
	v_and_b32_e32 v33, 0xffff0000, v120
	v_lshlrev_b32_e32 v34, 16, v121
	v_and_b32_e32 v35, 0xffff0000, v121
	v_lshlrev_b32_e32 v36, 16, v122
	v_and_b32_e32 v37, 0xffff0000, v122
	v_lshlrev_b32_e32 v38, 16, v123
	v_and_b32_e32 v39, 0xffff0000, v123
	v_pk_add_f32 v[22:23], v[22:23], v[34:35]
	v_pk_add_f32 v[20:21], v[20:21], v[32:33]
	v_pk_add_f32 v[32:33], v[18:19], v[38:39]
	v_pk_add_f32 v[34:35], v[16:17], v[36:37]
	v_pk_fma_f32 v[16:17], v[20:21], v[20:21], v[28:29]
	v_pk_fma_f32 v[18:19], v[22:23], v[22:23], v[30:31]
	v_pk_fma_f32 v[16:17], v[34:35], v[34:35], v[16:17]
	v_pk_fma_f32 v[18:19], v[32:33], v[32:33], v[18:19]
	v_add_f32_e32 v16, v16, v17
	v_add_f32_e32 v17, v18, v19
	v_add_f32_e32 v19, v16, v17
	v_mov_b32_e32 v30, v19
	s_nop 1
	v_permlane16_swap_b32 v30, v19
	v_lshl_add_u64 v[16:17], s[12:13], 0, v[212:213]
	v_lshl_add_u64 v[28:29], v[204:205], 1, v[16:17]
	global_store_dwordx4 v[28:29], v[24:27], off
	v_cvt_pk_bf16_f32 v18, v20, v21
	s_waitcnt lgkmcnt(0)
	v_add_f32_e32 v16, v19, v30
	v_mov_b32_e32 v17, v16
	s_nop 1
	v_permlane32_swap_b32 v17, v16
	v_cvt_pk_bf16_f32 v19, v22, v23
	v_cvt_pk_bf16_f32 v20, v34, v35
	v_cvt_pk_bf16_f32 v21, v32, v33
	global_store_dwordx4 v[28:29], v[18:21], off offset:256
	s_and_saveexec_b64 s[54:55], s[4:5]
	s_cbranch_execz .LBB0_1010
	v_lshlrev_b64 v[18:19], 6, v[210:211]
	v_lshl_add_u64 v[18:19], s[70:71], 0, v[18:19]
	v_lshl_add_u64 v[18:19], s[80:81], 2, v[18:19]
	s_lshl_b32 s10, s20, 2
	v_lshl_add_u64 v[18:19], v[18:19], 0, s[10:11]
	s_waitcnt lgkmcnt(0)
	v_add_f32_e32 v16, v16, v17
	global_store_dword v[18:19], v16, off
.LBB0_1010:
	s_or_b64 exec, exec, s[54:55]
	v_lshlrev_b32_e32 v16, 16, v132
	s_waitcnt lgkmcnt(0)
	v_and_b32_e32 v17, 0xffff0000, v132
	v_lshlrev_b32_e32 v18, 16, v133
	v_and_b32_e32 v19, 0xffff0000, v133
	v_lshlrev_b32_e32 v20, 16, v134
	v_and_b32_e32 v21, 0xffff0000, v134
	v_lshlrev_b32_e32 v22, 16, v135
	v_and_b32_e32 v23, 0xffff0000, v135
	v_pk_add_f32 v[14:15], v[14:15], v[18:19]
	v_pk_add_f32 v[12:13], v[12:13], v[16:17]
	v_pk_add_f32 v[16:17], v[10:11], v[22:23]
	v_pk_add_f32 v[18:19], v[8:9], v[20:21]
	v_cvt_pk_bf16_f32 v8, v12, v13
	v_cvt_pk_bf16_f32 v9, v14, v15
	v_pk_fma_f32 v[12:13], v[12:13], v[12:13], 0 op_sel_hi:[1,1,0]
	v_pk_fma_f32 v[14:15], v[14:15], v[14:15], 0 op_sel_hi:[1,1,0]
	v_cvt_pk_bf16_f32 v10, v18, v19
	v_cvt_pk_bf16_f32 v11, v16, v17
	v_pk_fma_f32 v[12:13], v[18:19], v[18:19], v[12:13]
	v_pk_fma_f32 v[14:15], v[16:17], v[16:17], v[14:15]
	v_lshlrev_b32_e32 v16, 16, v124
	v_and_b32_e32 v17, 0xffff0000, v124
	v_lshlrev_b32_e32 v18, 16, v125
	v_and_b32_e32 v19, 0xffff0000, v125
	v_lshlrev_b32_e32 v20, 16, v126
	v_and_b32_e32 v21, 0xffff0000, v126
	v_lshlrev_b32_e32 v22, 16, v127
	v_and_b32_e32 v23, 0xffff0000, v127
	v_pk_add_f32 v[6:7], v[6:7], v[18:19]
	v_pk_add_f32 v[4:5], v[4:5], v[16:17]
	v_pk_add_f32 v[16:17], v[2:3], v[22:23]
	v_pk_add_f32 v[18:19], v[0:1], v[20:21]
	v_pk_fma_f32 v[0:1], v[4:5], v[4:5], v[12:13]
	v_pk_fma_f32 v[2:3], v[6:7], v[6:7], v[14:15]
	v_pk_fma_f32 v[0:1], v[18:19], v[18:19], v[0:1]
	v_pk_fma_f32 v[2:3], v[16:17], v[16:17], v[2:3]
	v_add_f32_e32 v0, v0, v1
	v_add_f32_e32 v1, v2, v3
	v_add_f32_e32 v3, v0, v1
	v_mov_b32_e32 v14, v3
	s_nop 1
	v_permlane16_swap_b32 v14, v3
	v_lshl_add_u64 v[0:1], s[12:13], 0, v[208:209]
	v_lshl_add_u64 v[12:13], v[204:205], 1, v[0:1]
	global_store_dwordx4 v[12:13], v[8:11], off
	v_cvt_pk_bf16_f32 v2, v4, v5
	s_waitcnt lgkmcnt(0)
	v_add_f32_e32 v0, v3, v14
	v_mov_b32_e32 v1, v0
	s_nop 1
	v_permlane32_swap_b32 v1, v0
	v_cvt_pk_bf16_f32 v3, v6, v7
	v_cvt_pk_bf16_f32 v4, v18, v19
	v_cvt_pk_bf16_f32 v5, v16, v17
	global_store_dwordx4 v[12:13], v[2:5], off offset:256
	s_and_saveexec_b64 s[54:55], s[4:5]
	s_cbranch_execz .LBB0_1012
	v_lshlrev_b64 v[2:3], 6, v[206:207]
	v_lshl_add_u64 v[2:3], s[70:71], 0, v[2:3]
	v_lshl_add_u64 v[2:3], s[80:81], 2, v[2:3]
	s_lshl_b32 s10, s20, 2
	v_lshl_add_u64 v[2:3], v[2:3], 0, s[10:11]
	s_waitcnt lgkmcnt(0)
	v_add_f32_e32 v0, v0, v1
	global_store_dword v[2:3], v0, off

.LBB0_1302:
	v_lshl_or_b32 v204, s44, 8, v244
	v_lshl_add_u32 v234, s54, 8, v242
	v_ashrrev_i32_e32 v205, 31, v204
	v_lshlrev_b64 v[236:237], 1, v[204:205]
	v_ashrrev_i32_e32 v235, 31, v234
	v_lshl_add_u64 v[124:125], s[12:13], 0, v[236:237]
	v_lshlrev_b64 v[238:239], 11, v[234:235]
	v_lshl_add_u64 v[120:121], v[124:125], 0, v[238:239]
	global_load_dwordx4 v[188:191], v[120:121], off
	global_load_dwordx4 v[184:187], v[120:121], off offset:256
	v_or_b32_e32 v230, 16, v234
	v_ashrrev_i32_e32 v231, 31, v230
	v_or_b32_e32 v226, 32, v234
	v_lshlrev_b64 v[232:233], 11, v[230:231]
	v_ashrrev_i32_e32 v227, 31, v226
	v_or_b32_e32 v222, 48, v234
	v_lshl_add_u64 v[120:121], v[124:125], 0, v[232:233]
	v_lshlrev_b64 v[228:229], 11, v[226:227]
	v_ashrrev_i32_e32 v223, 31, v222
	v_add_u32_e32 v218, 0x80, v234
	global_load_dwordx4 v[180:183], v[120:121], off
	global_load_dwordx4 v[176:179], v[120:121], off offset:256
	v_lshl_add_u64 v[120:121], v[124:125], 0, v[228:229]
	v_lshlrev_b64 v[224:225], 11, v[222:223]
	v_ashrrev_i32_e32 v219, 31, v218
	v_add_u32_e32 v214, 0x90, v234
	global_load_dwordx4 v[172:175], v[120:121], off
	global_load_dwordx4 v[168:171], v[120:121], off offset:256
	v_lshl_add_u64 v[120:121], v[124:125], 0, v[224:225]
	v_lshlrev_b64 v[220:221], 11, v[218:219]
	v_ashrrev_i32_e32 v215, 31, v214
	v_add_u32_e32 v210, 0xa0, v234
	v_add_u32_e32 v206, 0xb0, v234
	global_load_dwordx4 v[164:167], v[120:121], off
	global_load_dwordx4 v[160:163], v[120:121], off offset:256
	v_lshl_add_u64 v[120:121], v[124:125], 0, v[220:221]
	v_lshlrev_b64 v[216:217], 11, v[214:215]
	v_ashrrev_i32_e32 v211, 31, v210
	v_ashrrev_i32_e32 v207, 31, v206
	global_load_dwordx4 v[156:159], v[120:121], off
	global_load_dwordx4 v[152:155], v[120:121], off offset:256
	v_lshl_add_u64 v[120:121], v[124:125], 0, v[216:217]
	v_lshlrev_b64 v[212:213], 11, v[210:211]
	v_lshlrev_b64 v[208:209], 11, v[206:207]
	global_load_dwordx4 v[148:151], v[120:121], off
	global_load_dwordx4 v[144:147], v[120:121], off offset:256
	v_lshl_add_u64 v[120:121], v[124:125], 0, v[212:213]
	v_lshl_add_u64 v[124:125], v[124:125], 0, v[208:209]
	global_load_dwordx4 v[128:131], v[120:121], off
	s_nop 0
	global_load_dwordx4 v[120:123], v[120:121], off offset:256
	s_nop 0
	global_load_dwordx4 v[132:135], v[124:125], off
	s_nop 0
	global_load_dwordx4 v[124:127], v[124:125], off offset:256
	v_lshl_add_u64 v[238:239], s[12:13], 0, v[238:239]
	v_lshl_add_u64 v[236:237], v[238:239], 0, v[236:237]
	s_lshl_b32 s76, s44, 2
	s_ashr_i32 s77, s76, 31
	s_waitcnt vmcnt(0)
	v_lshlrev_b32_e32 v250, 16, v188
	v_and_b32_e32 v251, 0xffff0000, v188
	v_lshlrev_b32_e32 v188, 16, v189
	v_and_b32_e32 v189, 0xffff0000, v189
	v_lshlrev_b32_e32 v252, 16, v190
	v_and_b32_e32 v253, 0xffff0000, v190
	v_lshlrev_b32_e32 v190, 16, v191
	v_and_b32_e32 v191, 0xffff0000, v191
	v_pk_fma_f32 v[142:143], v[142:143], 0.5, v[188:189] op_sel_hi:[1,0,1]
	v_pk_fma_f32 v[140:141], v[140:141], 0.5, v[250:251] op_sel_hi:[1,0,1]
	v_pk_fma_f32 v[188:189], v[138:139], 0.5, v[190:191] op_sel_hi:[1,0,1]
	v_pk_fma_f32 v[190:191], v[136:137], 0.5, v[252:253] op_sel_hi:[1,0,1]
	v_cvt_pk_bf16_f32 v136, v140, v141
	v_cvt_pk_bf16_f32 v137, v142, v143
	s_nop 0
	v_cvt_pk_bf16_f32 v138, v190, v191
	v_cvt_pk_bf16_f32 v139, v188, v189
	global_store_dwordx4 v[236:237], v[136:139], off
	s_nop 1
	v_pk_fma_f32 v[136:137], v[140:141], v[140:141], 0 op_sel_hi:[1,1,0]
	v_pk_fma_f32 v[138:139], v[142:143], v[142:143], 0 op_sel_hi:[1,1,0]
	v_lshlrev_b32_e32 v140, 16, v184
	v_and_b32_e32 v141, 0xffff0000, v184
	v_lshlrev_b32_e32 v142, 16, v185
	v_and_b32_e32 v143, 0xffff0000, v185
	v_lshlrev_b32_e32 v184, 16, v186
	v_and_b32_e32 v185, 0xffff0000, v186
	v_lshlrev_b32_e32 v186, 16, v187
	v_and_b32_e32 v187, 0xffff0000, v187
	v_pk_fma_f32 v[138:139], v[188:189], v[188:189], v[138:139]
	v_pk_fma_f32 v[136:137], v[190:191], v[190:191], v[136:137]
	v_pk_fma_f32 v[118:119], v[118:119], 0.5, v[142:143] op_sel_hi:[1,0,1]
	v_pk_fma_f32 v[116:117], v[116:117], 0.5, v[140:141] op_sel_hi:[1,0,1]
	v_pk_fma_f32 v[140:141], v[114:115], 0.5, v[186:187] op_sel_hi:[1,0,1]
	v_pk_fma_f32 v[142:143], v[112:113], 0.5, v[184:185] op_sel_hi:[1,0,1]
	v_cvt_pk_bf16_f32 v112, v116, v117
	v_cvt_pk_bf16_f32 v113, v118, v119
	s_nop 0
	v_cvt_pk_bf16_f32 v114, v142, v143
	v_cvt_pk_bf16_f32 v115, v140, v141
	global_store_dwordx4 v[236:237], v[112:115], off offset:256
	s_nop 1
	v_pk_fma_f32 v[112:113], v[116:117], v[116:117], v[136:137]
	v_pk_fma_f32 v[114:115], v[118:119], v[118:119], v[138:139]
	v_pk_fma_f32 v[112:113], v[142:143], v[142:143], v[112:113]
	v_pk_fma_f32 v[114:115], v[140:141], v[140:141], v[114:115]
	v_add_f32_e32 v112, v112, v113
	v_add_f32_e32 v113, v114, v115
	v_and_b32_e32 v114, 64, v248
	v_add_f32_e32 v113, v112, v113
	v_xor_b32_e32 v112, 16, v248
	v_add_u32_e32 v115, 64, v114
	v_cmp_lt_i32_e32 vcc, v112, v115
	s_nop 1
	v_cndmask_b32_e32 v112, v248, v112, vcc
	v_lshlrev_b32_e32 v112, 2, v112
	v_mov_b32_e32 v114, v113
	s_nop 1
	v_permlane16_swap_b32 v114, v113
	s_waitcnt lgkmcnt(0)
	v_add_f32_e32 v114, v113, v114
	v_xor_b32_e32 v113, 32, v248
	v_cmp_lt_i32_e32 vcc, v113, v115
	s_nop 1
	v_cndmask_b32_e32 v113, v248, v113, vcc
	v_lshlrev_b32_e32 v113, 2, v113
	v_mov_b32_e32 v115, v114
	s_nop 1
	v_permlane32_swap_b32 v115, v114
	s_and_saveexec_b64 s[54:55], s[4:5]
	s_cbranch_execz .LBB0_1304
	v_lshlrev_b64 v[116:117], 6, v[234:235]
	v_lshl_add_u64 v[116:117], s[70:71], 0, v[116:117]
	v_lshl_add_u64 v[116:117], s[76:77], 2, v[116:117]
	s_lshl_b32 s44, s20, 2
	v_lshl_add_u64 v[116:117], v[116:117], 0, s[44:45]
	s_waitcnt lgkmcnt(0)
	v_add_f32_e32 v114, v114, v115
	global_store_dword v[116:117], v114, off
.LBB0_1304:
	s_or_b64 exec, exec, s[54:55]
	v_lshlrev_b32_e32 v114, 16, v180
	s_waitcnt lgkmcnt(0)
	v_and_b32_e32 v115, 0xffff0000, v180
	v_lshlrev_b32_e32 v116, 16, v181
	v_and_b32_e32 v117, 0xffff0000, v181
	v_lshlrev_b32_e32 v118, 16, v182
	v_and_b32_e32 v119, 0xffff0000, v182
	v_lshlrev_b32_e32 v136, 16, v183
	v_and_b32_e32 v137, 0xffff0000, v183
	v_pk_fma_f32 v[110:111], v[110:111], 0.5, v[116:117] op_sel_hi:[1,0,1]
	v_pk_fma_f32 v[108:109], v[108:109], 0.5, v[114:115] op_sel_hi:[1,0,1]
	v_pk_fma_f32 v[114:115], v[106:107], 0.5, v[136:137] op_sel_hi:[1,0,1]
	v_pk_fma_f32 v[116:117], v[104:105], 0.5, v[118:119] op_sel_hi:[1,0,1]
	v_cvt_pk_bf16_f32 v104, v108, v109
	v_cvt_pk_bf16_f32 v105, v110, v111
	v_pk_fma_f32 v[108:109], v[108:109], v[108:109], 0 op_sel_hi:[1,1,0]
	v_pk_fma_f32 v[110:111], v[110:111], v[110:111], 0 op_sel_hi:[1,1,0]
	v_cvt_pk_bf16_f32 v106, v116, v117
	v_cvt_pk_bf16_f32 v107, v114, v115
	v_pk_fma_f32 v[108:109], v[116:117], v[116:117], v[108:109]
	v_pk_fma_f32 v[110:111], v[114:115], v[114:115], v[110:111]
	v_lshlrev_b32_e32 v114, 16, v176
	v_and_b32_e32 v115, 0xffff0000, v176
	v_lshlrev_b32_e32 v116, 16, v177
	v_and_b32_e32 v117, 0xffff0000, v177
	v_lshlrev_b32_e32 v118, 16, v178
	v_and_b32_e32 v119, 0xffff0000, v178
	v_lshlrev_b32_e32 v136, 16, v179
	v_and_b32_e32 v137, 0xffff0000, v179
	v_pk_fma_f32 v[102:103], v[102:103], 0.5, v[116:117] op_sel_hi:[1,0,1]
	v_pk_fma_f32 v[100:101], v[100:101], 0.5, v[114:115] op_sel_hi:[1,0,1]
	v_pk_fma_f32 v[114:115], v[98:99], 0.5, v[136:137] op_sel_hi:[1,0,1]
	v_pk_fma_f32 v[116:117], v[96:97], 0.5, v[118:119] op_sel_hi:[1,0,1]
	v_pk_fma_f32 v[96:97], v[100:101], v[100:101], v[108:109]
	v_pk_fma_f32 v[98:99], v[102:103], v[102:103], v[110:111]
	v_pk_fma_f32 v[96:97], v[116:117], v[116:117], v[96:97]
	v_pk_fma_f32 v[98:99], v[114:115], v[114:115], v[98:99]
	v_add_f32_e32 v96, v96, v97
	v_add_f32_e32 v97, v98, v99
	v_add_f32_e32 v99, v96, v97
	v_mov_b32_e32 v110, v99
	s_nop 1
	v_permlane16_swap_b32 v110, v99
	v_lshl_add_u64 v[96:97], s[12:13], 0, v[232:233]
	v_lshl_add_u64 v[108:109], v[204:205], 1, v[96:97]
	global_store_dwordx4 v[108:109], v[104:107], off
	v_cvt_pk_bf16_f32 v98, v100, v101
	s_waitcnt lgkmcnt(0)
	v_add_f32_e32 v96, v99, v110
	v_mov_b32_e32 v97, v96
	s_nop 1
	v_permlane32_swap_b32 v97, v96
	v_cvt_pk_bf16_f32 v99, v102, v103
	v_cvt_pk_bf16_f32 v100, v116, v117
	v_cvt_pk_bf16_f32 v101, v114, v115
	global_store_dwordx4 v[108:109], v[98:101], off offset:256
	s_and_saveexec_b64 s[54:55], s[4:5]
	s_cbranch_execz .LBB0_1306
	v_lshlrev_b64 v[98:99], 6, v[230:231]
	v_lshl_add_u64 v[98:99], s[70:71], 0, v[98:99]
	v_lshl_add_u64 v[98:99], s[76:77], 2, v[98:99]
	s_lshl_b32 s44, s20, 2
	v_lshl_add_u64 v[98:99], v[98:99], 0, s[44:45]
	s_waitcnt lgkmcnt(0)
	v_add_f32_e32 v96, v96, v97
	global_store_dword v[98:99], v96, off
.LBB0_1306:
	s_or_b64 exec, exec, s[54:55]
	v_lshlrev_b32_e32 v96, 16, v172
	s_waitcnt lgkmcnt(0)
	v_and_b32_e32 v97, 0xffff0000, v172
	v_lshlrev_b32_e32 v98, 16, v173
	v_and_b32_e32 v99, 0xffff0000, v173
	v_lshlrev_b32_e32 v100, 16, v174
	v_and_b32_e32 v101, 0xffff0000, v174
	v_lshlrev_b32_e32 v102, 16, v175
	v_and_b32_e32 v103, 0xffff0000, v175
	v_pk_fma_f32 v[94:95], v[94:95], 0.5, v[98:99] op_sel_hi:[1,0,1]
	v_pk_fma_f32 v[92:93], v[92:93], 0.5, v[96:97] op_sel_hi:[1,0,1]
	v_pk_fma_f32 v[96:97], v[90:91], 0.5, v[102:103] op_sel_hi:[1,0,1]
	v_pk_fma_f32 v[98:99], v[88:89], 0.5, v[100:101] op_sel_hi:[1,0,1]
	v_cvt_pk_bf16_f32 v88, v92, v93
	v_cvt_pk_bf16_f32 v89, v94, v95
	v_pk_fma_f32 v[92:93], v[92:93], v[92:93], 0 op_sel_hi:[1,1,0]
	v_pk_fma_f32 v[94:95], v[94:95], v[94:95], 0 op_sel_hi:[1,1,0]
	v_cvt_pk_bf16_f32 v90, v98, v99
	v_cvt_pk_bf16_f32 v91, v96, v97
	v_pk_fma_f32 v[92:93], v[98:99], v[98:99], v[92:93]
	v_pk_fma_f32 v[94:95], v[96:97], v[96:97], v[94:95]
	v_lshlrev_b32_e32 v96, 16, v168
	v_and_b32_e32 v97, 0xffff0000, v168
	v_lshlrev_b32_e32 v98, 16, v169
	v_and_b32_e32 v99, 0xffff0000, v169
	v_lshlrev_b32_e32 v100, 16, v170
	v_and_b32_e32 v101, 0xffff0000, v170
	v_lshlrev_b32_e32 v102, 16, v171
	v_and_b32_e32 v103, 0xffff0000, v171
	v_pk_fma_f32 v[86:87], v[86:87], 0.5, v[98:99] op_sel_hi:[1,0,1]
	v_pk_fma_f32 v[84:85], v[84:85], 0.5, v[96:97] op_sel_hi:[1,0,1]
	v_pk_fma_f32 v[96:97], v[82:83], 0.5, v[102:103] op_sel_hi:[1,0,1]
	v_pk_fma_f32 v[98:99], v[80:81], 0.5, v[100:101] op_sel_hi:[1,0,1]
	v_pk_fma_f32 v[80:81], v[84:85], v[84:85], v[92:93]
	v_pk_fma_f32 v[82:83], v[86:87], v[86:87], v[94:95]
	v_pk_fma_f32 v[80:81], v[98:99], v[98:99], v[80:81]
	v_pk_fma_f32 v[82:83], v[96:97], v[96:97], v[82:83]
	v_add_f32_e32 v80, v80, v81
	v_add_f32_e32 v81, v82, v83
	v_add_f32_e32 v83, v80, v81
	v_mov_b32_e32 v94, v83
	s_nop 1
	v_permlane16_swap_b32 v94, v83
	v_lshl_add_u64 v[80:81], s[12:13], 0, v[228:229]
	v_lshl_add_u64 v[92:93], v[204:205], 1, v[80:81]
	global_store_dwordx4 v[92:93], v[88:91], off
	v_cvt_pk_bf16_f32 v82, v84, v85
	s_waitcnt lgkmcnt(0)
	v_add_f32_e32 v80, v83, v94
	v_mov_b32_e32 v81, v80
	s_nop 1
	v_permlane32_swap_b32 v81, v80
	v_cvt_pk_bf16_f32 v83, v86, v87
	v_cvt_pk_bf16_f32 v84, v98, v99
	v_cvt_pk_bf16_f32 v85, v96, v97
	global_store_dwordx4 v[92:93], v[82:85], off offset:256
	s_and_saveexec_b64 s[54:55], s[4:5]
	s_cbranch_execz .LBB0_1308
	v_lshlrev_b64 v[82:83], 6, v[226:227]
	v_lshl_add_u64 v[82:83], s[70:71], 0, v[82:83]
	v_lshl_add_u64 v[82:83], s[76:77], 2, v[82:83]
	s_lshl_b32 s44, s20, 2
	v_lshl_add_u64 v[82:83], v[82:83], 0, s[44:45]
	s_waitcnt lgkmcnt(0)
	v_add_f32_e32 v80, v80, v81
	global_store_dword v[82:83], v80, off
.LBB0_1308:
	s_or_b64 exec, exec, s[54:55]
	v_lshlrev_b32_e32 v80, 16, v164
	s_waitcnt lgkmcnt(0)
	v_and_b32_e32 v81, 0xffff0000, v164
	v_lshlrev_b32_e32 v82, 16, v165
	v_and_b32_e32 v83, 0xffff0000, v165
	v_lshlrev_b32_e32 v84, 16, v166
	v_and_b32_e32 v85, 0xffff0000, v166
	v_lshlrev_b32_e32 v86, 16, v167
	v_and_b32_e32 v87, 0xffff0000, v167
	v_pk_fma_f32 v[78:79], v[78:79], 0.5, v[82:83] op_sel_hi:[1,0,1]
	v_pk_fma_f32 v[76:77], v[76:77], 0.5, v[80:81] op_sel_hi:[1,0,1]
	v_pk_fma_f32 v[80:81], v[74:75], 0.5, v[86:87] op_sel_hi:[1,0,1]
	v_pk_fma_f32 v[82:83], v[72:73], 0.5, v[84:85] op_sel_hi:[1,0,1]
	v_cvt_pk_bf16_f32 v72, v76, v77
	v_cvt_pk_bf16_f32 v73, v78, v79
	v_pk_fma_f32 v[76:77], v[76:77], v[76:77], 0 op_sel_hi:[1,1,0]
	v_pk_fma_f32 v[78:79], v[78:79], v[78:79], 0 op_sel_hi:[1,1,0]
	v_cvt_pk_bf16_f32 v74, v82, v83
	v_cvt_pk_bf16_f32 v75, v80, v81
	v_pk_fma_f32 v[76:77], v[82:83], v[82:83], v[76:77]
	v_pk_fma_f32 v[78:79], v[80:81], v[80:81], v[78:79]
	v_lshlrev_b32_e32 v80, 16, v160
	v_and_b32_e32 v81, 0xffff0000, v160
	v_lshlrev_b32_e32 v82, 16, v161
	v_and_b32_e32 v83, 0xffff0000, v161
	v_lshlrev_b32_e32 v84, 16, v162
	v_and_b32_e32 v85, 0xffff0000, v162
	v_lshlrev_b32_e32 v86, 16, v163
	v_and_b32_e32 v87, 0xffff0000, v163
	v_pk_fma_f32 v[70:71], v[70:71], 0.5, v[82:83] op_sel_hi:[1,0,1]
	v_pk_fma_f32 v[68:69], v[68:69], 0.5, v[80:81] op_sel_hi:[1,0,1]
	v_pk_fma_f32 v[80:81], v[66:67], 0.5, v[86:87] op_sel_hi:[1,0,1]
	v_pk_fma_f32 v[82:83], v[64:65], 0.5, v[84:85] op_sel_hi:[1,0,1]
	v_pk_fma_f32 v[64:65], v[68:69], v[68:69], v[76:77]
	v_pk_fma_f32 v[66:67], v[70:71], v[70:71], v[78:79]
	v_pk_fma_f32 v[64:65], v[82:83], v[82:83], v[64:65]
	v_pk_fma_f32 v[66:67], v[80:81], v[80:81], v[66:67]
	v_add_f32_e32 v64, v64, v65
	v_add_f32_e32 v65, v66, v67
	v_add_f32_e32 v67, v64, v65
	v_mov_b32_e32 v78, v67
	s_nop 1
	v_permlane16_swap_b32 v78, v67
	v_lshl_add_u64 v[64:65], s[12:13], 0, v[224:225]
	v_lshl_add_u64 v[76:77], v[204:205], 1, v[64:65]
	global_store_dwordx4 v[76:77], v[72:75], off
	v_cvt_pk_bf16_f32 v66, v68, v69
	s_waitcnt lgkmcnt(0)
	v_add_f32_e32 v64, v67, v78
	v_mov_b32_e32 v65, v64
	s_nop 1
	v_permlane32_swap_b32 v65, v64
	v_cvt_pk_bf16_f32 v67, v70, v71
	v_cvt_pk_bf16_f32 v68, v82, v83
	v_cvt_pk_bf16_f32 v69, v80, v81
	global_store_dwordx4 v[76:77], v[66:69], off offset:256
	s_and_saveexec_b64 s[54:55], s[4:5]
	s_cbranch_execz .LBB0_1310
	v_lshlrev_b64 v[66:67], 6, v[222:223]
	v_lshl_add_u64 v[66:67], s[70:71], 0, v[66:67]
	v_lshl_add_u64 v[66:67], s[76:77], 2, v[66:67]
	s_lshl_b32 s44, s20, 2
	v_lshl_add_u64 v[66:67], v[66:67], 0, s[44:45]
	s_waitcnt lgkmcnt(0)
	v_add_f32_e32 v64, v64, v65
	global_store_dword v[66:67], v64, off
.LBB0_1310:
	s_or_b64 exec, exec, s[54:55]
	v_lshlrev_b32_e32 v64, 16, v156
	s_waitcnt lgkmcnt(0)
	v_and_b32_e32 v65, 0xffff0000, v156
	v_lshlrev_b32_e32 v66, 16, v157
	v_and_b32_e32 v67, 0xffff0000, v157
	v_lshlrev_b32_e32 v68, 16, v158
	v_and_b32_e32 v69, 0xffff0000, v158
	v_lshlrev_b32_e32 v70, 16, v159
	v_and_b32_e32 v71, 0xffff0000, v159
	v_pk_fma_f32 v[62:63], v[62:63], 0.5, v[66:67] op_sel_hi:[1,0,1]
	v_pk_fma_f32 v[60:61], v[60:61], 0.5, v[64:65] op_sel_hi:[1,0,1]
	v_pk_fma_f32 v[64:65], v[58:59], 0.5, v[70:71] op_sel_hi:[1,0,1]
	v_pk_fma_f32 v[66:67], v[56:57], 0.5, v[68:69] op_sel_hi:[1,0,1]
	v_cvt_pk_bf16_f32 v56, v60, v61
	v_cvt_pk_bf16_f32 v57, v62, v63
	v_pk_fma_f32 v[60:61], v[60:61], v[60:61], 0 op_sel_hi:[1,1,0]
	v_pk_fma_f32 v[62:63], v[62:63], v[62:63], 0 op_sel_hi:[1,1,0]
	v_cvt_pk_bf16_f32 v58, v66, v67
	v_cvt_pk_bf16_f32 v59, v64, v65
	v_pk_fma_f32 v[60:61], v[66:67], v[66:67], v[60:61]
	v_pk_fma_f32 v[62:63], v[64:65], v[64:65], v[62:63]
	v_lshlrev_b32_e32 v64, 16, v152
	v_and_b32_e32 v65, 0xffff0000, v152
	v_lshlrev_b32_e32 v66, 16, v153
	v_and_b32_e32 v67, 0xffff0000, v153
	v_lshlrev_b32_e32 v68, 16, v154
	v_and_b32_e32 v69, 0xffff0000, v154
	v_lshlrev_b32_e32 v70, 16, v155
	v_and_b32_e32 v71, 0xffff0000, v155
	v_pk_fma_f32 v[54:55], v[54:55], 0.5, v[66:67] op_sel_hi:[1,0,1]
	v_pk_fma_f32 v[52:53], v[52:53], 0.5, v[64:65] op_sel_hi:[1,0,1]
	v_pk_fma_f32 v[64:65], v[50:51], 0.5, v[70:71] op_sel_hi:[1,0,1]
	v_pk_fma_f32 v[66:67], v[48:49], 0.5, v[68:69] op_sel_hi:[1,0,1]
	v_pk_fma_f32 v[48:49], v[52:53], v[52:53], v[60:61]
	v_pk_fma_f32 v[50:51], v[54:55], v[54:55], v[62:63]
	v_pk_fma_f32 v[48:49], v[66:67], v[66:67], v[48:49]
	v_pk_fma_f32 v[50:51], v[64:65], v[64:65], v[50:51]
	v_add_f32_e32 v48, v48, v49
	v_add_f32_e32 v49, v50, v51
	v_add_f32_e32 v51, v48, v49
	v_mov_b32_e32 v62, v51
	s_nop 1
	v_permlane16_swap_b32 v62, v51
	v_lshl_add_u64 v[48:49], s[12:13], 0, v[220:221]
	v_lshl_add_u64 v[60:61], v[204:205], 1, v[48:49]
	global_store_dwordx4 v[60:61], v[56:59], off
	v_cvt_pk_bf16_f32 v50, v52, v53
	s_waitcnt lgkmcnt(0)
	v_add_f32_e32 v48, v51, v62
	v_mov_b32_e32 v49, v48
	s_nop 1
	v_permlane32_swap_b32 v49, v48
	v_cvt_pk_bf16_f32 v51, v54, v55
	v_cvt_pk_bf16_f32 v52, v66, v67
	v_cvt_pk_bf16_f32 v53, v64, v65
	global_store_dwordx4 v[60:61], v[50:53], off offset:256
	s_and_saveexec_b64 s[54:55], s[4:5]
	s_cbranch_execz .LBB0_1312
	v_lshlrev_b64 v[50:51], 6, v[218:219]
	v_lshl_add_u64 v[50:51], s[70:71], 0, v[50:51]
	v_lshl_add_u64 v[50:51], s[76:77], 2, v[50:51]
	s_lshl_b32 s44, s20, 2
	v_lshl_add_u64 v[50:51], v[50:51], 0, s[44:45]
	s_waitcnt lgkmcnt(0)
	v_add_f32_e32 v48, v48, v49
	global_store_dword v[50:51], v48, off
.LBB0_1312:
	s_or_b64 exec, exec, s[54:55]
	v_lshlrev_b32_e32 v48, 16, v148
	s_waitcnt lgkmcnt(0)
	v_and_b32_e32 v49, 0xffff0000, v148
	v_lshlrev_b32_e32 v50, 16, v149
	v_and_b32_e32 v51, 0xffff0000, v149
	v_lshlrev_b32_e32 v52, 16, v150
	v_and_b32_e32 v53, 0xffff0000, v150
	v_lshlrev_b32_e32 v54, 16, v151
	v_and_b32_e32 v55, 0xffff0000, v151
	v_pk_fma_f32 v[46:47], v[46:47], 0.5, v[50:51] op_sel_hi:[1,0,1]
	v_pk_fma_f32 v[44:45], v[44:45], 0.5, v[48:49] op_sel_hi:[1,0,1]
	v_pk_fma_f32 v[48:49], v[42:43], 0.5, v[54:55] op_sel_hi:[1,0,1]
	v_pk_fma_f32 v[50:51], v[40:41], 0.5, v[52:53] op_sel_hi:[1,0,1]
	v_cvt_pk_bf16_f32 v40, v44, v45
	v_cvt_pk_bf16_f32 v41, v46, v47
	v_pk_fma_f32 v[44:45], v[44:45], v[44:45], 0 op_sel_hi:[1,1,0]
	v_pk_fma_f32 v[46:47], v[46:47], v[46:47], 0 op_sel_hi:[1,1,0]
	v_cvt_pk_bf16_f32 v42, v50, v51
	v_cvt_pk_bf16_f32 v43, v48, v49
	v_pk_fma_f32 v[44:45], v[50:51], v[50:51], v[44:45]
	v_pk_fma_f32 v[46:47], v[48:49], v[48:49], v[46:47]
	v_lshlrev_b32_e32 v48, 16, v144
	v_and_b32_e32 v49, 0xffff0000, v144
	v_lshlrev_b32_e32 v50, 16, v145
	v_and_b32_e32 v51, 0xffff0000, v145
	v_lshlrev_b32_e32 v52, 16, v146
	v_and_b32_e32 v53, 0xffff0000, v146
	v_lshlrev_b32_e32 v54, 16, v147
	v_and_b32_e32 v55, 0xffff0000, v147
	v_pk_fma_f32 v[38:39], v[38:39], 0.5, v[50:51] op_sel_hi:[1,0,1]
	v_pk_fma_f32 v[36:37], v[36:37], 0.5, v[48:49] op_sel_hi:[1,0,1]
	v_pk_fma_f32 v[48:49], v[34:35], 0.5, v[54:55] op_sel_hi:[1,0,1]
	v_pk_fma_f32 v[50:51], v[32:33], 0.5, v[52:53] op_sel_hi:[1,0,1]
	v_pk_fma_f32 v[32:33], v[36:37], v[36:37], v[44:45]
	v_pk_fma_f32 v[34:35], v[38:39], v[38:39], v[46:47]
	v_pk_fma_f32 v[32:33], v[50:51], v[50:51], v[32:33]
	v_pk_fma_f32 v[34:35], v[48:49], v[48:49], v[34:35]
	v_add_f32_e32 v32, v32, v33
	v_add_f32_e32 v33, v34, v35
	v_add_f32_e32 v35, v32, v33
	v_mov_b32_e32 v46, v35
	s_nop 1
	v_permlane16_swap_b32 v46, v35
	v_lshl_add_u64 v[32:33], s[12:13], 0, v[216:217]
	v_lshl_add_u64 v[44:45], v[204:205], 1, v[32:33]
	global_store_dwordx4 v[44:45], v[40:43], off
	v_cvt_pk_bf16_f32 v34, v36, v37
	s_waitcnt lgkmcnt(0)
	v_add_f32_e32 v32, v35, v46
	v_mov_b32_e32 v33, v32
	s_nop 1
	v_permlane32_swap_b32 v33, v32
	v_cvt_pk_bf16_f32 v35, v38, v39
	v_cvt_pk_bf16_f32 v36, v50, v51
	v_cvt_pk_bf16_f32 v37, v48, v49
	global_store_dwordx4 v[44:45], v[34:37], off offset:256
	s_and_saveexec_b64 s[54:55], s[4:5]
	s_cbranch_execz .LBB0_1314
	v_lshlrev_b64 v[34:35], 6, v[214:215]
	v_lshl_add_u64 v[34:35], s[70:71], 0, v[34:35]
	v_lshl_add_u64 v[34:35], s[76:77], 2, v[34:35]
	s_lshl_b32 s44, s20, 2
	v_lshl_add_u64 v[34:35], v[34:35], 0, s[44:45]
	s_waitcnt lgkmcnt(0)
	v_add_f32_e32 v32, v32, v33
	global_store_dword v[34:35], v32, off
.LBB0_1314:
	s_or_b64 exec, exec, s[54:55]
	v_lshlrev_b32_e32 v32, 16, v128
	s_waitcnt lgkmcnt(0)
	v_and_b32_e32 v33, 0xffff0000, v128
	v_lshlrev_b32_e32 v34, 16, v129
	v_and_b32_e32 v35, 0xffff0000, v129
	v_lshlrev_b32_e32 v36, 16, v130
	v_and_b32_e32 v37, 0xffff0000, v130
	v_lshlrev_b32_e32 v38, 16, v131
	v_and_b32_e32 v39, 0xffff0000, v131
	v_pk_fma_f32 v[30:31], v[30:31], 0.5, v[34:35] op_sel_hi:[1,0,1]
	v_pk_fma_f32 v[28:29], v[28:29], 0.5, v[32:33] op_sel_hi:[1,0,1]
	v_pk_fma_f32 v[32:33], v[26:27], 0.5, v[38:39] op_sel_hi:[1,0,1]
	v_pk_fma_f32 v[34:35], v[24:25], 0.5, v[36:37] op_sel_hi:[1,0,1]
	v_cvt_pk_bf16_f32 v24, v28, v29
	v_cvt_pk_bf16_f32 v25, v30, v31
	v_pk_fma_f32 v[28:29], v[28:29], v[28:29], 0 op_sel_hi:[1,1,0]
	v_pk_fma_f32 v[30:31], v[30:31], v[30:31], 0 op_sel_hi:[1,1,0]
	v_cvt_pk_bf16_f32 v26, v34, v35
	v_cvt_pk_bf16_f32 v27, v32, v33
	v_pk_fma_f32 v[28:29], v[34:35], v[34:35], v[28:29]
	v_pk_fma_f32 v[30:31], v[32:33], v[32:33], v[30:31]
	v_lshlrev_b32_e32 v32, 16, v120
	v_and_b32_e32 v33, 0xffff0000, v120
	v_lshlrev_b32_e32 v34, 16, v121
	v_and_b32_e32 v35, 0xffff0000, v121
	v_lshlrev_b32_e32 v36, 16, v122
	v_and_b32_e32 v37, 0xffff0000, v122
	v_lshlrev_b32_e32 v38, 16, v123
	v_and_b32_e32 v39, 0xffff0000, v123
	v_pk_fma_f32 v[22:23], v[22:23], 0.5, v[34:35] op_sel_hi:[1,0,1]
	v_pk_fma_f32 v[20:21], v[20:21], 0.5, v[32:33] op_sel_hi:[1,0,1]
	v_pk_fma_f32 v[32:33], v[18:19], 0.5, v[38:39] op_sel_hi:[1,0,1]
	v_pk_fma_f32 v[34:35], v[16:17], 0.5, v[36:37] op_sel_hi:[1,0,1]
	v_pk_fma_f32 v[16:17], v[20:21], v[20:21], v[28:29]
	v_pk_fma_f32 v[18:19], v[22:23], v[22:23], v[30:31]
	v_pk_fma_f32 v[16:17], v[34:35], v[34:35], v[16:17]
	v_pk_fma_f32 v[18:19], v[32:33], v[32:33], v[18:19]
	v_add_f32_e32 v16, v16, v17
	v_add_f32_e32 v17, v18, v19
	v_add_f32_e32 v19, v16, v17
	v_mov_b32_e32 v30, v19
	s_nop 1
	v_permlane16_swap_b32 v30, v19
	v_lshl_add_u64 v[16:17], s[12:13], 0, v[212:213]
	v_lshl_add_u64 v[28:29], v[204:205], 1, v[16:17]
	global_store_dwordx4 v[28:29], v[24:27], off
	v_cvt_pk_bf16_f32 v18, v20, v21
	s_waitcnt lgkmcnt(0)
	v_add_f32_e32 v16, v19, v30
	v_mov_b32_e32 v17, v16
	s_nop 1
	v_permlane32_swap_b32 v17, v16
	v_cvt_pk_bf16_f32 v19, v22, v23
	v_cvt_pk_bf16_f32 v20, v34, v35
	v_cvt_pk_bf16_f32 v21, v32, v33
	global_store_dwordx4 v[28:29], v[18:21], off offset:256
	s_and_saveexec_b64 s[54:55], s[4:5]
	s_cbranch_execz .LBB0_1316
	v_lshlrev_b64 v[18:19], 6, v[210:211]
	v_lshl_add_u64 v[18:19], s[70:71], 0, v[18:19]
	v_lshl_add_u64 v[18:19], s[76:77], 2, v[18:19]
	s_lshl_b32 s44, s20, 2
	v_lshl_add_u64 v[18:19], v[18:19], 0, s[44:45]
	s_waitcnt lgkmcnt(0)
	v_add_f32_e32 v16, v16, v17
	global_store_dword v[18:19], v16, off
.LBB0_1316:
	s_or_b64 exec, exec, s[54:55]
	v_lshlrev_b32_e32 v16, 16, v132
	s_waitcnt lgkmcnt(0)
	v_and_b32_e32 v17, 0xffff0000, v132
	v_lshlrev_b32_e32 v18, 16, v133
	v_and_b32_e32 v19, 0xffff0000, v133
	v_lshlrev_b32_e32 v20, 16, v134
	v_and_b32_e32 v21, 0xffff0000, v134
	v_lshlrev_b32_e32 v22, 16, v135
	v_and_b32_e32 v23, 0xffff0000, v135
	v_pk_fma_f32 v[14:15], v[14:15], 0.5, v[18:19] op_sel_hi:[1,0,1]
	v_pk_fma_f32 v[12:13], v[12:13], 0.5, v[16:17] op_sel_hi:[1,0,1]
	v_pk_fma_f32 v[16:17], v[10:11], 0.5, v[22:23] op_sel_hi:[1,0,1]
	v_pk_fma_f32 v[18:19], v[8:9], 0.5, v[20:21] op_sel_hi:[1,0,1]
	v_cvt_pk_bf16_f32 v8, v12, v13
	v_cvt_pk_bf16_f32 v9, v14, v15
	v_pk_fma_f32 v[12:13], v[12:13], v[12:13], 0 op_sel_hi:[1,1,0]
	v_pk_fma_f32 v[14:15], v[14:15], v[14:15], 0 op_sel_hi:[1,1,0]
	v_cvt_pk_bf16_f32 v10, v18, v19
	v_cvt_pk_bf16_f32 v11, v16, v17
	v_pk_fma_f32 v[12:13], v[18:19], v[18:19], v[12:13]
	v_pk_fma_f32 v[14:15], v[16:17], v[16:17], v[14:15]
	v_lshlrev_b32_e32 v16, 16, v124
	v_and_b32_e32 v17, 0xffff0000, v124
	v_lshlrev_b32_e32 v18, 16, v125
	v_and_b32_e32 v19, 0xffff0000, v125
	v_lshlrev_b32_e32 v20, 16, v126
	v_and_b32_e32 v21, 0xffff0000, v126
	v_lshlrev_b32_e32 v22, 16, v127
	v_and_b32_e32 v23, 0xffff0000, v127
	v_pk_fma_f32 v[6:7], v[6:7], 0.5, v[18:19] op_sel_hi:[1,0,1]
	v_pk_fma_f32 v[4:5], v[4:5], 0.5, v[16:17] op_sel_hi:[1,0,1]
	v_pk_fma_f32 v[16:17], v[2:3], 0.5, v[22:23] op_sel_hi:[1,0,1]
	v_pk_fma_f32 v[18:19], v[0:1], 0.5, v[20:21] op_sel_hi:[1,0,1]
	v_pk_fma_f32 v[0:1], v[4:5], v[4:5], v[12:13]
	v_pk_fma_f32 v[2:3], v[6:7], v[6:7], v[14:15]
	v_pk_fma_f32 v[0:1], v[18:19], v[18:19], v[0:1]
	v_pk_fma_f32 v[2:3], v[16:17], v[16:17], v[2:3]
	v_add_f32_e32 v0, v0, v1
	v_add_f32_e32 v1, v2, v3
	v_add_f32_e32 v3, v0, v1
	v_mov_b32_e32 v14, v3
	s_nop 1
	v_permlane16_swap_b32 v14, v3
	v_lshl_add_u64 v[0:1], s[12:13], 0, v[208:209]
	v_lshl_add_u64 v[12:13], v[204:205], 1, v[0:1]
	global_store_dwordx4 v[12:13], v[8:11], off
	v_cvt_pk_bf16_f32 v2, v4, v5
	s_waitcnt lgkmcnt(0)
	v_add_f32_e32 v0, v3, v14
	v_mov_b32_e32 v1, v0
	s_nop 1
	v_permlane32_swap_b32 v1, v0
	v_cvt_pk_bf16_f32 v3, v6, v7
	v_cvt_pk_bf16_f32 v4, v18, v19
	v_cvt_pk_bf16_f32 v5, v16, v17
	global_store_dwordx4 v[12:13], v[2:5], off offset:256
	s_and_saveexec_b64 s[54:55], s[4:5]
	s_cbranch_execz .LBB0_1318
	v_lshlrev_b64 v[2:3], 6, v[206:207]
	v_lshl_add_u64 v[2:3], s[70:71], 0, v[2:3]
	v_lshl_add_u64 v[2:3], s[76:77], 2, v[2:3]
	s_lshl_b32 s44, s20, 2
	v_lshl_add_u64 v[2:3], v[2:3], 0, s[44:45]
	s_waitcnt lgkmcnt(0)
	v_add_f32_e32 v0, v0, v1
	global_store_dword v[2:3], v0, off

.LBB0_2040:
	v_lshl_or_b32 v204, s10, 8, v244
	v_lshl_add_u32 v234, s74, 8, v242
	v_ashrrev_i32_e32 v205, 31, v204
	v_lshlrev_b64 v[236:237], 1, v[204:205]
	v_ashrrev_i32_e32 v235, 31, v234
	v_lshl_add_u64 v[124:125], s[12:13], 0, v[236:237]
	v_lshlrev_b64 v[238:239], 11, v[234:235]
	v_lshl_add_u64 v[120:121], v[124:125], 0, v[238:239]
	global_load_dwordx4 v[188:191], v[120:121], off
	global_load_dwordx4 v[184:187], v[120:121], off offset:256
	v_or_b32_e32 v230, 16, v234
	v_ashrrev_i32_e32 v231, 31, v230
	v_or_b32_e32 v226, 32, v234
	v_lshlrev_b64 v[232:233], 11, v[230:231]
	v_ashrrev_i32_e32 v227, 31, v226
	v_or_b32_e32 v222, 48, v234
	v_lshl_add_u64 v[120:121], v[124:125], 0, v[232:233]
	v_lshlrev_b64 v[228:229], 11, v[226:227]
	v_ashrrev_i32_e32 v223, 31, v222
	v_add_u32_e32 v218, 0x80, v234
	global_load_dwordx4 v[180:183], v[120:121], off
	global_load_dwordx4 v[176:179], v[120:121], off offset:256
	v_lshl_add_u64 v[120:121], v[124:125], 0, v[228:229]
	v_lshlrev_b64 v[224:225], 11, v[222:223]
	v_ashrrev_i32_e32 v219, 31, v218
	v_add_u32_e32 v214, 0x90, v234
	global_load_dwordx4 v[172:175], v[120:121], off
	global_load_dwordx4 v[168:171], v[120:121], off offset:256
	v_lshl_add_u64 v[120:121], v[124:125], 0, v[224:225]
	v_lshlrev_b64 v[220:221], 11, v[218:219]
	v_ashrrev_i32_e32 v215, 31, v214
	v_add_u32_e32 v210, 0xa0, v234
	v_add_u32_e32 v206, 0xb0, v234
	global_load_dwordx4 v[164:167], v[120:121], off
	global_load_dwordx4 v[160:163], v[120:121], off offset:256
	v_lshl_add_u64 v[120:121], v[124:125], 0, v[220:221]
	v_lshlrev_b64 v[216:217], 11, v[214:215]
	v_ashrrev_i32_e32 v211, 31, v210
	v_ashrrev_i32_e32 v207, 31, v206
	global_load_dwordx4 v[156:159], v[120:121], off
	global_load_dwordx4 v[152:155], v[120:121], off offset:256
	v_lshl_add_u64 v[120:121], v[124:125], 0, v[216:217]
	v_lshlrev_b64 v[212:213], 11, v[210:211]
	v_lshlrev_b64 v[208:209], 11, v[206:207]
	global_load_dwordx4 v[148:151], v[120:121], off
	global_load_dwordx4 v[144:147], v[120:121], off offset:256
	v_lshl_add_u64 v[120:121], v[124:125], 0, v[212:213]
	v_lshl_add_u64 v[124:125], v[124:125], 0, v[208:209]
	global_load_dwordx4 v[128:131], v[120:121], off
	s_nop 0
	global_load_dwordx4 v[120:123], v[120:121], off offset:256
	s_nop 0
	global_load_dwordx4 v[132:135], v[124:125], off
	s_nop 0
	global_load_dwordx4 v[124:127], v[124:125], off offset:256
	v_lshl_add_u64 v[238:239], s[12:13], 0, v[238:239]
	v_lshl_add_u64 v[236:237], v[238:239], 0, v[236:237]
	s_lshl_b32 s74, s10, 2
	s_ashr_i32 s75, s74, 31
	s_waitcnt vmcnt(0)
	v_lshlrev_b32_e32 v250, 16, v188
	v_and_b32_e32 v251, 0xffff0000, v188
	v_lshlrev_b32_e32 v188, 16, v189
	v_and_b32_e32 v189, 0xffff0000, v189
	v_lshlrev_b32_e32 v252, 16, v190
	v_and_b32_e32 v253, 0xffff0000, v190
	v_lshlrev_b32_e32 v190, 16, v191
	v_and_b32_e32 v191, 0xffff0000, v191
	v_pk_add_f32 v[142:143], v[142:143], v[188:189]
	v_pk_add_f32 v[140:141], v[140:141], v[250:251]
	v_pk_add_f32 v[188:189], v[138:139], v[190:191]
	v_pk_add_f32 v[190:191], v[136:137], v[252:253]
	v_cvt_pk_bf16_f32 v136, v140, v141
	v_cvt_pk_bf16_f32 v137, v142, v143
	s_nop 0
	v_cvt_pk_bf16_f32 v138, v190, v191
	v_cvt_pk_bf16_f32 v139, v188, v189
	global_store_dwordx4 v[236:237], v[136:139], off
	s_nop 1
	v_pk_fma_f32 v[136:137], v[140:141], v[140:141], 0 op_sel_hi:[1,1,0]
	v_pk_fma_f32 v[138:139], v[142:143], v[142:143], 0 op_sel_hi:[1,1,0]
	v_lshlrev_b32_e32 v140, 16, v184
	v_and_b32_e32 v141, 0xffff0000, v184
	v_lshlrev_b32_e32 v142, 16, v185
	v_and_b32_e32 v143, 0xffff0000, v185
	v_lshlrev_b32_e32 v184, 16, v186
	v_and_b32_e32 v185, 0xffff0000, v186
	v_lshlrev_b32_e32 v186, 16, v187
	v_and_b32_e32 v187, 0xffff0000, v187
	v_pk_fma_f32 v[138:139], v[188:189], v[188:189], v[138:139]
	v_pk_fma_f32 v[136:137], v[190:191], v[190:191], v[136:137]
	v_pk_add_f32 v[118:119], v[118:119], v[142:143]
	v_pk_add_f32 v[116:117], v[116:117], v[140:141]
	v_pk_add_f32 v[140:141], v[114:115], v[186:187]
	v_pk_add_f32 v[142:143], v[112:113], v[184:185]
	v_cvt_pk_bf16_f32 v112, v116, v117
	v_cvt_pk_bf16_f32 v113, v118, v119
	s_nop 0
	v_cvt_pk_bf16_f32 v114, v142, v143
	v_cvt_pk_bf16_f32 v115, v140, v141
	global_store_dwordx4 v[236:237], v[112:115], off offset:256
	s_nop 1
	v_pk_fma_f32 v[112:113], v[116:117], v[116:117], v[136:137]
	v_pk_fma_f32 v[114:115], v[118:119], v[118:119], v[138:139]
	v_pk_fma_f32 v[112:113], v[142:143], v[142:143], v[112:113]
	v_pk_fma_f32 v[114:115], v[140:141], v[140:141], v[114:115]
	v_add_f32_e32 v112, v112, v113
	v_add_f32_e32 v113, v114, v115
	v_and_b32_e32 v114, 64, v248
	v_add_f32_e32 v113, v112, v113
	v_xor_b32_e32 v112, 16, v248
	v_add_u32_e32 v115, 64, v114
	v_cmp_lt_i32_e32 vcc, v112, v115
	s_nop 1
	v_cndmask_b32_e32 v112, v248, v112, vcc
	v_lshlrev_b32_e32 v112, 2, v112
	v_mov_b32_e32 v114, v113
	s_nop 1
	v_permlane16_swap_b32 v114, v113
	s_waitcnt lgkmcnt(0)
	v_add_f32_e32 v114, v113, v114
	v_xor_b32_e32 v113, 32, v248
	v_cmp_lt_i32_e32 vcc, v113, v115
	s_nop 1
	v_cndmask_b32_e32 v113, v248, v113, vcc
	v_lshlrev_b32_e32 v113, 2, v113
	v_mov_b32_e32 v115, v114
	s_nop 1
	v_permlane32_swap_b32 v115, v114
	s_and_saveexec_b64 s[54:55], s[4:5]
	s_cbranch_execz .LBB0_2042
	v_lshlrev_b64 v[116:117], 6, v[234:235]
	v_lshl_add_u64 v[116:117], s[70:71], 0, v[116:117]
	v_lshl_add_u64 v[116:117], s[74:75], 2, v[116:117]
	s_lshl_b32 s10, s20, 2
	v_lshl_add_u64 v[116:117], v[116:117], 0, s[10:11]
	s_waitcnt lgkmcnt(0)
	v_add_f32_e32 v114, v114, v115
	global_store_dword v[116:117], v114, off
.LBB0_2042:
	s_or_b64 exec, exec, s[54:55]
	v_lshlrev_b32_e32 v114, 16, v180
	s_waitcnt lgkmcnt(0)
	v_and_b32_e32 v115, 0xffff0000, v180
	v_lshlrev_b32_e32 v116, 16, v181
	v_and_b32_e32 v117, 0xffff0000, v181
	v_lshlrev_b32_e32 v118, 16, v182
	v_and_b32_e32 v119, 0xffff0000, v182
	v_lshlrev_b32_e32 v136, 16, v183
	v_and_b32_e32 v137, 0xffff0000, v183
	v_pk_add_f32 v[110:111], v[110:111], v[116:117]
	v_pk_add_f32 v[108:109], v[108:109], v[114:115]
	v_pk_add_f32 v[114:115], v[106:107], v[136:137]
	v_pk_add_f32 v[116:117], v[104:105], v[118:119]
	v_cvt_pk_bf16_f32 v104, v108, v109
	v_cvt_pk_bf16_f32 v105, v110, v111
	v_pk_fma_f32 v[108:109], v[108:109], v[108:109], 0 op_sel_hi:[1,1,0]
	v_pk_fma_f32 v[110:111], v[110:111], v[110:111], 0 op_sel_hi:[1,1,0]
	v_cvt_pk_bf16_f32 v106, v116, v117
	v_cvt_pk_bf16_f32 v107, v114, v115
	v_pk_fma_f32 v[108:109], v[116:117], v[116:117], v[108:109]
	v_pk_fma_f32 v[110:111], v[114:115], v[114:115], v[110:111]
	v_lshlrev_b32_e32 v114, 16, v176
	v_and_b32_e32 v115, 0xffff0000, v176
	v_lshlrev_b32_e32 v116, 16, v177
	v_and_b32_e32 v117, 0xffff0000, v177
	v_lshlrev_b32_e32 v118, 16, v178
	v_and_b32_e32 v119, 0xffff0000, v178
	v_lshlrev_b32_e32 v136, 16, v179
	v_and_b32_e32 v137, 0xffff0000, v179
	v_pk_add_f32 v[102:103], v[102:103], v[116:117]
	v_pk_add_f32 v[100:101], v[100:101], v[114:115]
	v_pk_add_f32 v[114:115], v[98:99], v[136:137]
	v_pk_add_f32 v[116:117], v[96:97], v[118:119]
	v_pk_fma_f32 v[96:97], v[100:101], v[100:101], v[108:109]
	v_pk_fma_f32 v[98:99], v[102:103], v[102:103], v[110:111]
	v_pk_fma_f32 v[96:97], v[116:117], v[116:117], v[96:97]
	v_pk_fma_f32 v[98:99], v[114:115], v[114:115], v[98:99]
	v_add_f32_e32 v96, v96, v97
	v_add_f32_e32 v97, v98, v99
	v_add_f32_e32 v99, v96, v97
	v_mov_b32_e32 v110, v99
	s_nop 1
	v_permlane16_swap_b32 v110, v99
	v_lshl_add_u64 v[96:97], s[12:13], 0, v[232:233]
	v_lshl_add_u64 v[108:109], v[204:205], 1, v[96:97]
	global_store_dwordx4 v[108:109], v[104:107], off
	v_cvt_pk_bf16_f32 v98, v100, v101
	s_waitcnt lgkmcnt(0)
	v_add_f32_e32 v96, v99, v110
	v_mov_b32_e32 v97, v96
	s_nop 1
	v_permlane32_swap_b32 v97, v96
	v_cvt_pk_bf16_f32 v99, v102, v103
	v_cvt_pk_bf16_f32 v100, v116, v117
	v_cvt_pk_bf16_f32 v101, v114, v115
	global_store_dwordx4 v[108:109], v[98:101], off offset:256
	s_and_saveexec_b64 s[54:55], s[4:5]
	s_cbranch_execz .LBB0_2044
	v_lshlrev_b64 v[98:99], 6, v[230:231]
	v_lshl_add_u64 v[98:99], s[70:71], 0, v[98:99]
	v_lshl_add_u64 v[98:99], s[74:75], 2, v[98:99]
	s_lshl_b32 s10, s20, 2
	v_lshl_add_u64 v[98:99], v[98:99], 0, s[10:11]
	s_waitcnt lgkmcnt(0)
	v_add_f32_e32 v96, v96, v97
	global_store_dword v[98:99], v96, off
.LBB0_2044:
	s_or_b64 exec, exec, s[54:55]
	v_lshlrev_b32_e32 v96, 16, v172
	s_waitcnt lgkmcnt(0)
	v_and_b32_e32 v97, 0xffff0000, v172
	v_lshlrev_b32_e32 v98, 16, v173
	v_and_b32_e32 v99, 0xffff0000, v173
	v_lshlrev_b32_e32 v100, 16, v174
	v_and_b32_e32 v101, 0xffff0000, v174
	v_lshlrev_b32_e32 v102, 16, v175
	v_and_b32_e32 v103, 0xffff0000, v175
	v_pk_add_f32 v[94:95], v[94:95], v[98:99]
	v_pk_add_f32 v[92:93], v[92:93], v[96:97]
	v_pk_add_f32 v[96:97], v[90:91], v[102:103]
	v_pk_add_f32 v[98:99], v[88:89], v[100:101]
	v_cvt_pk_bf16_f32 v88, v92, v93
	v_cvt_pk_bf16_f32 v89, v94, v95
	v_pk_fma_f32 v[92:93], v[92:93], v[92:93], 0 op_sel_hi:[1,1,0]
	v_pk_fma_f32 v[94:95], v[94:95], v[94:95], 0 op_sel_hi:[1,1,0]
	v_cvt_pk_bf16_f32 v90, v98, v99
	v_cvt_pk_bf16_f32 v91, v96, v97
	v_pk_fma_f32 v[92:93], v[98:99], v[98:99], v[92:93]
	v_pk_fma_f32 v[94:95], v[96:97], v[96:97], v[94:95]
	v_lshlrev_b32_e32 v96, 16, v168
	v_and_b32_e32 v97, 0xffff0000, v168
	v_lshlrev_b32_e32 v98, 16, v169
	v_and_b32_e32 v99, 0xffff0000, v169
	v_lshlrev_b32_e32 v100, 16, v170
	v_and_b32_e32 v101, 0xffff0000, v170
	v_lshlrev_b32_e32 v102, 16, v171
	v_and_b32_e32 v103, 0xffff0000, v171
	v_pk_add_f32 v[86:87], v[86:87], v[98:99]
	v_pk_add_f32 v[84:85], v[84:85], v[96:97]
	v_pk_add_f32 v[96:97], v[82:83], v[102:103]
	v_pk_add_f32 v[98:99], v[80:81], v[100:101]
	v_pk_fma_f32 v[80:81], v[84:85], v[84:85], v[92:93]
	v_pk_fma_f32 v[82:83], v[86:87], v[86:87], v[94:95]
	v_pk_fma_f32 v[80:81], v[98:99], v[98:99], v[80:81]
	v_pk_fma_f32 v[82:83], v[96:97], v[96:97], v[82:83]
	v_add_f32_e32 v80, v80, v81
	v_add_f32_e32 v81, v82, v83
	v_add_f32_e32 v83, v80, v81
	v_mov_b32_e32 v94, v83
	s_nop 1
	v_permlane16_swap_b32 v94, v83
	v_lshl_add_u64 v[80:81], s[12:13], 0, v[228:229]
	v_lshl_add_u64 v[92:93], v[204:205], 1, v[80:81]
	global_store_dwordx4 v[92:93], v[88:91], off
	v_cvt_pk_bf16_f32 v82, v84, v85
	s_waitcnt lgkmcnt(0)
	v_add_f32_e32 v80, v83, v94
	v_mov_b32_e32 v81, v80
	s_nop 1
	v_permlane32_swap_b32 v81, v80
	v_cvt_pk_bf16_f32 v83, v86, v87
	v_cvt_pk_bf16_f32 v84, v98, v99
	v_cvt_pk_bf16_f32 v85, v96, v97
	global_store_dwordx4 v[92:93], v[82:85], off offset:256
	s_and_saveexec_b64 s[54:55], s[4:5]
	s_cbranch_execz .LBB0_2046
	v_lshlrev_b64 v[82:83], 6, v[226:227]
	v_lshl_add_u64 v[82:83], s[70:71], 0, v[82:83]
	v_lshl_add_u64 v[82:83], s[74:75], 2, v[82:83]
	s_lshl_b32 s10, s20, 2
	v_lshl_add_u64 v[82:83], v[82:83], 0, s[10:11]
	s_waitcnt lgkmcnt(0)
	v_add_f32_e32 v80, v80, v81
	global_store_dword v[82:83], v80, off
.LBB0_2046:
	s_or_b64 exec, exec, s[54:55]
	v_lshlrev_b32_e32 v80, 16, v164
	s_waitcnt lgkmcnt(0)
	v_and_b32_e32 v81, 0xffff0000, v164
	v_lshlrev_b32_e32 v82, 16, v165
	v_and_b32_e32 v83, 0xffff0000, v165
	v_lshlrev_b32_e32 v84, 16, v166
	v_and_b32_e32 v85, 0xffff0000, v166
	v_lshlrev_b32_e32 v86, 16, v167
	v_and_b32_e32 v87, 0xffff0000, v167
	v_pk_add_f32 v[78:79], v[78:79], v[82:83]
	v_pk_add_f32 v[76:77], v[76:77], v[80:81]
	v_pk_add_f32 v[80:81], v[74:75], v[86:87]
	v_pk_add_f32 v[82:83], v[72:73], v[84:85]
	v_cvt_pk_bf16_f32 v72, v76, v77
	v_cvt_pk_bf16_f32 v73, v78, v79
	v_pk_fma_f32 v[76:77], v[76:77], v[76:77], 0 op_sel_hi:[1,1,0]
	v_pk_fma_f32 v[78:79], v[78:79], v[78:79], 0 op_sel_hi:[1,1,0]
	v_cvt_pk_bf16_f32 v74, v82, v83
	v_cvt_pk_bf16_f32 v75, v80, v81
	v_pk_fma_f32 v[76:77], v[82:83], v[82:83], v[76:77]
	v_pk_fma_f32 v[78:79], v[80:81], v[80:81], v[78:79]
	v_lshlrev_b32_e32 v80, 16, v160
	v_and_b32_e32 v81, 0xffff0000, v160
	v_lshlrev_b32_e32 v82, 16, v161
	v_and_b32_e32 v83, 0xffff0000, v161
	v_lshlrev_b32_e32 v84, 16, v162
	v_and_b32_e32 v85, 0xffff0000, v162
	v_lshlrev_b32_e32 v86, 16, v163
	v_and_b32_e32 v87, 0xffff0000, v163
	v_pk_add_f32 v[70:71], v[70:71], v[82:83]
	v_pk_add_f32 v[68:69], v[68:69], v[80:81]
	v_pk_add_f32 v[80:81], v[66:67], v[86:87]
	v_pk_add_f32 v[82:83], v[64:65], v[84:85]
	v_pk_fma_f32 v[64:65], v[68:69], v[68:69], v[76:77]
	v_pk_fma_f32 v[66:67], v[70:71], v[70:71], v[78:79]
	v_pk_fma_f32 v[64:65], v[82:83], v[82:83], v[64:65]
	v_pk_fma_f32 v[66:67], v[80:81], v[80:81], v[66:67]
	v_add_f32_e32 v64, v64, v65
	v_add_f32_e32 v65, v66, v67
	v_add_f32_e32 v67, v64, v65
	v_mov_b32_e32 v78, v67
	s_nop 1
	v_permlane16_swap_b32 v78, v67
	v_lshl_add_u64 v[64:65], s[12:13], 0, v[224:225]
	v_lshl_add_u64 v[76:77], v[204:205], 1, v[64:65]
	global_store_dwordx4 v[76:77], v[72:75], off
	v_cvt_pk_bf16_f32 v66, v68, v69
	s_waitcnt lgkmcnt(0)
	v_add_f32_e32 v64, v67, v78
	v_mov_b32_e32 v65, v64
	s_nop 1
	v_permlane32_swap_b32 v65, v64
	v_cvt_pk_bf16_f32 v67, v70, v71
	v_cvt_pk_bf16_f32 v68, v82, v83
	v_cvt_pk_bf16_f32 v69, v80, v81
	global_store_dwordx4 v[76:77], v[66:69], off offset:256
	s_and_saveexec_b64 s[54:55], s[4:5]
	s_cbranch_execz .LBB0_2048
	v_lshlrev_b64 v[66:67], 6, v[222:223]
	v_lshl_add_u64 v[66:67], s[70:71], 0, v[66:67]
	v_lshl_add_u64 v[66:67], s[74:75], 2, v[66:67]
	s_lshl_b32 s10, s20, 2
	v_lshl_add_u64 v[66:67], v[66:67], 0, s[10:11]
	s_waitcnt lgkmcnt(0)
	v_add_f32_e32 v64, v64, v65
	global_store_dword v[66:67], v64, off
.LBB0_2048:
	s_or_b64 exec, exec, s[54:55]
	v_lshlrev_b32_e32 v64, 16, v156
	s_waitcnt lgkmcnt(0)
	v_and_b32_e32 v65, 0xffff0000, v156
	v_lshlrev_b32_e32 v66, 16, v157
	v_and_b32_e32 v67, 0xffff0000, v157
	v_lshlrev_b32_e32 v68, 16, v158
	v_and_b32_e32 v69, 0xffff0000, v158
	v_lshlrev_b32_e32 v70, 16, v159
	v_and_b32_e32 v71, 0xffff0000, v159
	v_pk_add_f32 v[62:63], v[62:63], v[66:67]
	v_pk_add_f32 v[60:61], v[60:61], v[64:65]
	v_pk_add_f32 v[64:65], v[58:59], v[70:71]
	v_pk_add_f32 v[66:67], v[56:57], v[68:69]
	v_cvt_pk_bf16_f32 v56, v60, v61
	v_cvt_pk_bf16_f32 v57, v62, v63
	v_pk_fma_f32 v[60:61], v[60:61], v[60:61], 0 op_sel_hi:[1,1,0]
	v_pk_fma_f32 v[62:63], v[62:63], v[62:63], 0 op_sel_hi:[1,1,0]
	v_cvt_pk_bf16_f32 v58, v66, v67
	v_cvt_pk_bf16_f32 v59, v64, v65
	v_pk_fma_f32 v[60:61], v[66:67], v[66:67], v[60:61]
	v_pk_fma_f32 v[62:63], v[64:65], v[64:65], v[62:63]
	v_lshlrev_b32_e32 v64, 16, v152
	v_and_b32_e32 v65, 0xffff0000, v152
	v_lshlrev_b32_e32 v66, 16, v153
	v_and_b32_e32 v67, 0xffff0000, v153
	v_lshlrev_b32_e32 v68, 16, v154
	v_and_b32_e32 v69, 0xffff0000, v154
	v_lshlrev_b32_e32 v70, 16, v155
	v_and_b32_e32 v71, 0xffff0000, v155
	v_pk_add_f32 v[54:55], v[54:55], v[66:67]
	v_pk_add_f32 v[52:53], v[52:53], v[64:65]
	v_pk_add_f32 v[64:65], v[50:51], v[70:71]
	v_pk_add_f32 v[66:67], v[48:49], v[68:69]
	v_pk_fma_f32 v[48:49], v[52:53], v[52:53], v[60:61]
	v_pk_fma_f32 v[50:51], v[54:55], v[54:55], v[62:63]
	v_pk_fma_f32 v[48:49], v[66:67], v[66:67], v[48:49]
	v_pk_fma_f32 v[50:51], v[64:65], v[64:65], v[50:51]
	v_add_f32_e32 v48, v48, v49
	v_add_f32_e32 v49, v50, v51
	v_add_f32_e32 v51, v48, v49
	v_mov_b32_e32 v62, v51
	s_nop 1
	v_permlane16_swap_b32 v62, v51
	v_lshl_add_u64 v[48:49], s[12:13], 0, v[220:221]
	v_lshl_add_u64 v[60:61], v[204:205], 1, v[48:49]
	global_store_dwordx4 v[60:61], v[56:59], off
	v_cvt_pk_bf16_f32 v50, v52, v53
	s_waitcnt lgkmcnt(0)
	v_add_f32_e32 v48, v51, v62
	v_mov_b32_e32 v49, v48
	s_nop 1
	v_permlane32_swap_b32 v49, v48
	v_cvt_pk_bf16_f32 v51, v54, v55
	v_cvt_pk_bf16_f32 v52, v66, v67
	v_cvt_pk_bf16_f32 v53, v64, v65
	global_store_dwordx4 v[60:61], v[50:53], off offset:256
	s_and_saveexec_b64 s[54:55], s[4:5]
	s_cbranch_execz .LBB0_2050
	v_lshlrev_b64 v[50:51], 6, v[218:219]
	v_lshl_add_u64 v[50:51], s[70:71], 0, v[50:51]
	v_lshl_add_u64 v[50:51], s[74:75], 2, v[50:51]
	s_lshl_b32 s10, s20, 2
	v_lshl_add_u64 v[50:51], v[50:51], 0, s[10:11]
	s_waitcnt lgkmcnt(0)
	v_add_f32_e32 v48, v48, v49
	global_store_dword v[50:51], v48, off
.LBB0_2050:
	s_or_b64 exec, exec, s[54:55]
	v_lshlrev_b32_e32 v48, 16, v148
	s_waitcnt lgkmcnt(0)
	v_and_b32_e32 v49, 0xffff0000, v148
	v_lshlrev_b32_e32 v50, 16, v149
	v_and_b32_e32 v51, 0xffff0000, v149
	v_lshlrev_b32_e32 v52, 16, v150
	v_and_b32_e32 v53, 0xffff0000, v150
	v_lshlrev_b32_e32 v54, 16, v151
	v_and_b32_e32 v55, 0xffff0000, v151
	v_pk_add_f32 v[46:47], v[46:47], v[50:51]
	v_pk_add_f32 v[44:45], v[44:45], v[48:49]
	v_pk_add_f32 v[48:49], v[42:43], v[54:55]
	v_pk_add_f32 v[50:51], v[40:41], v[52:53]
	v_cvt_pk_bf16_f32 v40, v44, v45
	v_cvt_pk_bf16_f32 v41, v46, v47
	v_pk_fma_f32 v[44:45], v[44:45], v[44:45], 0 op_sel_hi:[1,1,0]
	v_pk_fma_f32 v[46:47], v[46:47], v[46:47], 0 op_sel_hi:[1,1,0]
	v_cvt_pk_bf16_f32 v42, v50, v51
	v_cvt_pk_bf16_f32 v43, v48, v49
	v_pk_fma_f32 v[44:45], v[50:51], v[50:51], v[44:45]
	v_pk_fma_f32 v[46:47], v[48:49], v[48:49], v[46:47]
	v_lshlrev_b32_e32 v48, 16, v144
	v_and_b32_e32 v49, 0xffff0000, v144
	v_lshlrev_b32_e32 v50, 16, v145
	v_and_b32_e32 v51, 0xffff0000, v145
	v_lshlrev_b32_e32 v52, 16, v146
	v_and_b32_e32 v53, 0xffff0000, v146
	v_lshlrev_b32_e32 v54, 16, v147
	v_and_b32_e32 v55, 0xffff0000, v147
	v_pk_add_f32 v[38:39], v[38:39], v[50:51]
	v_pk_add_f32 v[36:37], v[36:37], v[48:49]
	v_pk_add_f32 v[48:49], v[34:35], v[54:55]
	v_pk_add_f32 v[50:51], v[32:33], v[52:53]
	v_pk_fma_f32 v[32:33], v[36:37], v[36:37], v[44:45]
	v_pk_fma_f32 v[34:35], v[38:39], v[38:39], v[46:47]
	v_pk_fma_f32 v[32:33], v[50:51], v[50:51], v[32:33]
	v_pk_fma_f32 v[34:35], v[48:49], v[48:49], v[34:35]
	v_add_f32_e32 v32, v32, v33
	v_add_f32_e32 v33, v34, v35
	v_add_f32_e32 v35, v32, v33
	v_mov_b32_e32 v46, v35
	s_nop 1
	v_permlane16_swap_b32 v46, v35
	v_lshl_add_u64 v[32:33], s[12:13], 0, v[216:217]
	v_lshl_add_u64 v[44:45], v[204:205], 1, v[32:33]
	global_store_dwordx4 v[44:45], v[40:43], off
	v_cvt_pk_bf16_f32 v34, v36, v37
	s_waitcnt lgkmcnt(0)
	v_add_f32_e32 v32, v35, v46
	v_mov_b32_e32 v33, v32
	s_nop 1
	v_permlane32_swap_b32 v33, v32
	v_cvt_pk_bf16_f32 v35, v38, v39
	v_cvt_pk_bf16_f32 v36, v50, v51
	v_cvt_pk_bf16_f32 v37, v48, v49
	global_store_dwordx4 v[44:45], v[34:37], off offset:256
	s_and_saveexec_b64 s[54:55], s[4:5]
	s_cbranch_execz .LBB0_2052
	v_lshlrev_b64 v[34:35], 6, v[214:215]
	v_lshl_add_u64 v[34:35], s[70:71], 0, v[34:35]
	v_lshl_add_u64 v[34:35], s[74:75], 2, v[34:35]
	s_lshl_b32 s10, s20, 2
	v_lshl_add_u64 v[34:35], v[34:35], 0, s[10:11]
	s_waitcnt lgkmcnt(0)
	v_add_f32_e32 v32, v32, v33
	global_store_dword v[34:35], v32, off
.LBB0_2052:
	s_or_b64 exec, exec, s[54:55]
	v_lshlrev_b32_e32 v32, 16, v128
	s_waitcnt lgkmcnt(0)
	v_and_b32_e32 v33, 0xffff0000, v128
	v_lshlrev_b32_e32 v34, 16, v129
	v_and_b32_e32 v35, 0xffff0000, v129
	v_lshlrev_b32_e32 v36, 16, v130
	v_and_b32_e32 v37, 0xffff0000, v130
	v_lshlrev_b32_e32 v38, 16, v131
	v_and_b32_e32 v39, 0xffff0000, v131
	v_pk_add_f32 v[30:31], v[30:31], v[34:35]
	v_pk_add_f32 v[28:29], v[28:29], v[32:33]
	v_pk_add_f32 v[32:33], v[26:27], v[38:39]
	v_pk_add_f32 v[34:35], v[24:25], v[36:37]
	v_cvt_pk_bf16_f32 v24, v28, v29
	v_cvt_pk_bf16_f32 v25, v30, v31
	v_pk_fma_f32 v[28:29], v[28:29], v[28:29], 0 op_sel_hi:[1,1,0]
	v_pk_fma_f32 v[30:31], v[30:31], v[30:31], 0 op_sel_hi:[1,1,0]
	v_cvt_pk_bf16_f32 v26, v34, v35
	v_cvt_pk_bf16_f32 v27, v32, v33
	v_pk_fma_f32 v[28:29], v[34:35], v[34:35], v[28:29]
	v_pk_fma_f32 v[30:31], v[32:33], v[32:33], v[30:31]
	v_lshlrev_b32_e32 v32, 16, v120
	v_and_b32_e32 v33, 0xffff0000, v120
	v_lshlrev_b32_e32 v34, 16, v121
	v_and_b32_e32 v35, 0xffff0000, v121
	v_lshlrev_b32_e32 v36, 16, v122
	v_and_b32_e32 v37, 0xffff0000, v122
	v_lshlrev_b32_e32 v38, 16, v123
	v_and_b32_e32 v39, 0xffff0000, v123
	v_pk_add_f32 v[22:23], v[22:23], v[34:35]
	v_pk_add_f32 v[20:21], v[20:21], v[32:33]
	v_pk_add_f32 v[32:33], v[18:19], v[38:39]
	v_pk_add_f32 v[34:35], v[16:17], v[36:37]
	v_pk_fma_f32 v[16:17], v[20:21], v[20:21], v[28:29]
	v_pk_fma_f32 v[18:19], v[22:23], v[22:23], v[30:31]
	v_pk_fma_f32 v[16:17], v[34:35], v[34:35], v[16:17]
	v_pk_fma_f32 v[18:19], v[32:33], v[32:33], v[18:19]
	v_add_f32_e32 v16, v16, v17
	v_add_f32_e32 v17, v18, v19
	v_add_f32_e32 v19, v16, v17
	v_mov_b32_e32 v30, v19
	s_nop 1
	v_permlane16_swap_b32 v30, v19
	v_lshl_add_u64 v[16:17], s[12:13], 0, v[212:213]
	v_lshl_add_u64 v[28:29], v[204:205], 1, v[16:17]
	global_store_dwordx4 v[28:29], v[24:27], off
	v_cvt_pk_bf16_f32 v18, v20, v21
	s_waitcnt lgkmcnt(0)
	v_add_f32_e32 v16, v19, v30
	v_mov_b32_e32 v17, v16
	s_nop 1
	v_permlane32_swap_b32 v17, v16
	v_cvt_pk_bf16_f32 v19, v22, v23
	v_cvt_pk_bf16_f32 v20, v34, v35
	v_cvt_pk_bf16_f32 v21, v32, v33
	global_store_dwordx4 v[28:29], v[18:21], off offset:256
	s_and_saveexec_b64 s[54:55], s[4:5]
	s_cbranch_execz .LBB0_2054
	v_lshlrev_b64 v[18:19], 6, v[210:211]
	v_lshl_add_u64 v[18:19], s[70:71], 0, v[18:19]
	v_lshl_add_u64 v[18:19], s[74:75], 2, v[18:19]
	s_lshl_b32 s10, s20, 2
	v_lshl_add_u64 v[18:19], v[18:19], 0, s[10:11]
	s_waitcnt lgkmcnt(0)
	v_add_f32_e32 v16, v16, v17
	global_store_dword v[18:19], v16, off
.LBB0_2054:
	s_or_b64 exec, exec, s[54:55]
	v_lshlrev_b32_e32 v16, 16, v132
	s_waitcnt lgkmcnt(0)
	v_and_b32_e32 v17, 0xffff0000, v132
	v_lshlrev_b32_e32 v18, 16, v133
	v_and_b32_e32 v19, 0xffff0000, v133
	v_lshlrev_b32_e32 v20, 16, v134
	v_and_b32_e32 v21, 0xffff0000, v134
	v_lshlrev_b32_e32 v22, 16, v135
	v_and_b32_e32 v23, 0xffff0000, v135
	v_pk_add_f32 v[14:15], v[14:15], v[18:19]
	v_pk_add_f32 v[12:13], v[12:13], v[16:17]
	v_pk_add_f32 v[16:17], v[10:11], v[22:23]
	v_pk_add_f32 v[18:19], v[8:9], v[20:21]
	v_cvt_pk_bf16_f32 v8, v12, v13
	v_cvt_pk_bf16_f32 v9, v14, v15
	v_pk_fma_f32 v[12:13], v[12:13], v[12:13], 0 op_sel_hi:[1,1,0]
	v_pk_fma_f32 v[14:15], v[14:15], v[14:15], 0 op_sel_hi:[1,1,0]
	v_cvt_pk_bf16_f32 v10, v18, v19
	v_cvt_pk_bf16_f32 v11, v16, v17
	v_pk_fma_f32 v[12:13], v[18:19], v[18:19], v[12:13]
	v_pk_fma_f32 v[14:15], v[16:17], v[16:17], v[14:15]
	v_lshlrev_b32_e32 v16, 16, v124
	v_and_b32_e32 v17, 0xffff0000, v124
	v_lshlrev_b32_e32 v18, 16, v125
	v_and_b32_e32 v19, 0xffff0000, v125
	v_lshlrev_b32_e32 v20, 16, v126
	v_and_b32_e32 v21, 0xffff0000, v126
	v_lshlrev_b32_e32 v22, 16, v127
	v_and_b32_e32 v23, 0xffff0000, v127
	v_pk_add_f32 v[6:7], v[6:7], v[18:19]
	v_pk_add_f32 v[4:5], v[4:5], v[16:17]
	v_pk_add_f32 v[16:17], v[2:3], v[22:23]
	v_pk_add_f32 v[18:19], v[0:1], v[20:21]
	v_pk_fma_f32 v[0:1], v[4:5], v[4:5], v[12:13]
	v_pk_fma_f32 v[2:3], v[6:7], v[6:7], v[14:15]
	v_pk_fma_f32 v[0:1], v[18:19], v[18:19], v[0:1]
	v_pk_fma_f32 v[2:3], v[16:17], v[16:17], v[2:3]
	v_add_f32_e32 v0, v0, v1
	v_add_f32_e32 v1, v2, v3
	v_add_f32_e32 v3, v0, v1
	v_mov_b32_e32 v14, v3
	s_nop 1
	v_permlane16_swap_b32 v14, v3
	v_lshl_add_u64 v[0:1], s[12:13], 0, v[208:209]
	v_lshl_add_u64 v[12:13], v[204:205], 1, v[0:1]
	global_store_dwordx4 v[12:13], v[8:11], off
	v_cvt_pk_bf16_f32 v2, v4, v5
	s_waitcnt lgkmcnt(0)
	v_add_f32_e32 v0, v3, v14
	v_mov_b32_e32 v1, v0
	s_nop 1
	v_permlane32_swap_b32 v1, v0
	v_cvt_pk_bf16_f32 v3, v6, v7
	v_cvt_pk_bf16_f32 v4, v18, v19
	v_cvt_pk_bf16_f32 v5, v16, v17
	global_store_dwordx4 v[12:13], v[2:5], off offset:256
	s_and_saveexec_b64 s[54:55], s[4:5]
	s_cbranch_execz .LBB0_2056
	v_lshlrev_b64 v[2:3], 6, v[206:207]
	v_lshl_add_u64 v[2:3], s[70:71], 0, v[2:3]
	v_lshl_add_u64 v[2:3], s[74:75], 2, v[2:3]
	s_lshl_b32 s10, s20, 2
	v_lshl_add_u64 v[2:3], v[2:3], 0, s[10:11]
	s_waitcnt lgkmcnt(0)
	v_add_f32_e32 v0, v0, v1
	global_store_dword v[2:3], v0, off
